# stack2 + P1 sample mini-GEMM loads batched + P8 epilogue conv-weight loads requested early
# baseline (speedup 1.0000x reference)
; template <int NKS, bool ATILED = false, bool FFN = false, bool HALF = false, class EF> ...
;     ...
;         const int rb = pc / ncb, cb = pc - rb * ncb;
;         const bf16* a0 = ATILED ? A + (size_t)(MP + RB * rb + c16) * 64 : A + (size_t)(RB * rb + c16) * K + w * kw + 8 * kq;
;         const bf16* b0 = Wt + (size_t)((cb >> 2) * 256 + 32 * (cb & 3) + c16) * K + w * kw + 8 * kq;
;         f32x4 acc[MI][4];
; #pragma unroll
;         for (int mi = 0; mi < MI; ++mi)
; #pragma unroll
;             for (int ni = 0; ni < 4; ++ni) acc[mi][ni] = (f32x4){0.f, 0.f, 0.f, 0.f};
;         constexpr int SB = NS < 4 ? NS : 4;
; #pragma unroll 1
;         for (int s0 = 0; s0 < NS; s0 += SB) {
;             bf16x8 Af[SB][MI], Bf[SB][4];
; #pragma unroll
;             for (int j = 0; j < SB; ++j) if (s0 + j < NS) { const int s = s0 + j;
;                 if (ATILED) { const int kk = w * kw + 32 * s + 8 * kq; const bf16* at = a0 + (size_t)(kk >> 6) * MTOT * 64 + (kk & 63);
; #pragma unroll
;                     for (int mi = 0; mi < MI; ++mi) Af[j][mi] = *(const bf16x8*)(at + 16 * mi * 64); }
;                 else {
; #pragma unroll
;                     for (int mi = 0; mi < MI; ++mi) Af[j][mi] = *(const bf16x8*)(a0 + (size_t)(16 * mi) * K + 32 * s); }
; #pragma unroll
;                 for (int ni = 0; ni < 4; ++ni) Bf[j][ni] = *(const bf16x8*)(b0 + (size_t)(16 * (ni & 1) + 128 * (ni >> 1)) * K + 32 * s); }
;             asm volatile("s_waitcnt vmcnt(0)" ::: "memory");
; #pragma unroll
;             for (int j = 0; j < SB; ++j) if (s0 + j < NS) {
; #pragma unroll
;                 for (int mi = 0; mi < MI; ++mi)
; #pragma unroll
;                     for (int ni = 0; ni < 4; ++ni) acc[mi][ni] = __builtin_amdgcn_mfma_f32_16x16x32_bf16(Af[j][mi], Bf[j][ni], acc[mi][ni], 0, 0, 0); }
;         }
.LBB0_255:
	s_ashr_i32 s0, s29, 31
	s_lshr_b32 s0, s0, 27
	s_add_i32 s0, s29, s0
	s_ashr_i32 s1, s0, 5
	s_lshl_b32 s0, s1, 6
	s_lshl_b32 s1, s1, 11
	s_sub_i32 s30, s22, s1
	s_and_b32 s1, s30, 0xffffff00
	s_and_b32 s12, s20, 0x60
	v_or_b32_e32 v2, s0, v188
	s_or_b32 s1, s12, s1
	v_ashrrev_i32_e32 v3, 31, v2
	v_or_b32_e32 v6, s1, v188
	v_lshlrev_b64 v[2:3], 11, v[2:3]
	v_ashrrev_i32_e32 v7, 31, v6
	v_lshl_add_u64 v[4:5], v[18:19], 0, v[2:3]
	v_lshlrev_b64 v[2:3], 11, v[6:7]
	v_lshl_add_u64 v[8:9], v[20:21], 0, v[2:3]
	v_add_co_u32_e32 v26, vcc, s28, v8
	s_mov_b32 s1, 0x40000
	s_nop 0
	v_addc_co_u32_e32 v27, vcc, 0, v9, vcc
	v_add_co_u32_e32 v12, vcc, s1, v8
	s_mov_b32 s1, 0x48000
	s_nop 0
	v_addc_co_u32_e32 v13, vcc, 0, v9, vcc
	v_add_co_u32_e32 v14, vcc, s1, v8
	s_mov_b32 s1, 0x10000
	s_nop 0
	v_addc_co_u32_e32 v15, vcc, 0, v9, vcc
	v_add_co_u32_e32 v10, vcc, s28, v4
	s_nop 0
	s_nop 0
	v_addc_co_u32_e32 v11, vcc, 0, v5, vcc
	v_add_co_u32_e32 v6, vcc, s1, v4
	s_mov_b32 s1, 0x18000
	s_nop 0
	v_addc_co_u32_e32 v7, vcc, 0, v5, vcc
	v_add_co_u32_e32 v2, vcc, s1, v4
	s_nop 1
	v_addc_co_u32_e32 v3, vcc, 0, v5, vcc
	v_add_u32_e32 v16, s30, v22
	global_load_dwordx4 v[110:113], v[4:5], off
	global_load_dwordx4 v[114:117], v[10:11], off
	global_load_dwordx4 v[118:121], v[6:7], off
	global_load_dwordx4 v[122:125], v[2:3], off
	global_load_dwordx4 v[126:129], v[8:9], off
	global_load_dwordx4 v[130:133], v[26:27], off
	global_load_dwordx4 v[134:137], v[12:13], off
	global_load_dwordx4 v[138:141], v[14:15], off
	global_load_dwordx4 v[142:145], v[4:5], off offset:64
	global_load_dwordx4 v[146:149], v[10:11], off offset:64
	global_load_dwordx4 v[150:153], v[6:7], off offset:64
	global_load_dwordx4 v[154:157], v[2:3], off offset:64
	global_load_dwordx4 v[158:161], v[8:9], off offset:64
	global_load_dwordx4 v[162:165], v[26:27], off offset:64
	global_load_dwordx4 v[166:169], v[12:13], off offset:64
	global_load_dwordx4 v[170:173], v[14:15], off offset:64
	global_load_dwordx4 v[174:177], v[4:5], off offset:128
	global_load_dwordx4 v[178:181], v[10:11], off offset:128
	global_load_dwordx4 v[182:185], v[6:7], off offset:128
	global_load_dwordx4 v[198:201], v[2:3], off offset:128
	global_load_dwordx4 v[202:205], v[8:9], off offset:128
	global_load_dwordx4 v[206:209], v[26:27], off offset:128
	global_load_dwordx4 v[210:213], v[12:13], off offset:128
	global_load_dwordx4 v[214:217], v[14:15], off offset:128
	s_waitcnt vmcnt(16)
	v_mfma_f32_16x16x32_bf16 v[46:49], v[110:113], v[126:129], 0
	v_mfma_f32_16x16x32_bf16 v[50:53], v[110:113], v[130:133], 0
	v_mfma_f32_16x16x32_bf16 v[54:57], v[110:113], v[134:137], 0
	v_mfma_f32_16x16x32_bf16 v[58:61], v[110:113], v[138:141], 0
	v_mfma_f32_16x16x32_bf16 v[62:65], v[114:117], v[126:129], 0
	v_mfma_f32_16x16x32_bf16 v[66:69], v[114:117], v[130:133], 0
	v_mfma_f32_16x16x32_bf16 v[70:73], v[114:117], v[134:137], 0
	v_mfma_f32_16x16x32_bf16 v[74:77], v[114:117], v[138:141], 0
	v_mfma_f32_16x16x32_bf16 v[78:81], v[118:121], v[126:129], 0
	v_mfma_f32_16x16x32_bf16 v[82:85], v[118:121], v[130:133], 0
	v_mfma_f32_16x16x32_bf16 v[86:89], v[118:121], v[134:137], 0
	v_mfma_f32_16x16x32_bf16 v[90:93], v[118:121], v[138:141], 0
	v_mfma_f32_16x16x32_bf16 v[94:97], v[122:125], v[126:129], 0
	v_mfma_f32_16x16x32_bf16 v[98:101], v[122:125], v[130:133], 0
	v_mfma_f32_16x16x32_bf16 v[102:105], v[122:125], v[134:137], 0
	v_mfma_f32_16x16x32_bf16 v[106:109], v[122:125], v[138:141], 0
	global_load_dwordx4 v[110:113], v[4:5], off offset:192
	global_load_dwordx4 v[114:117], v[10:11], off offset:192
	global_load_dwordx4 v[118:121], v[6:7], off offset:192
	global_load_dwordx4 v[122:125], v[2:3], off offset:192
	global_load_dwordx4 v[126:129], v[8:9], off offset:192
	global_load_dwordx4 v[130:133], v[26:27], off offset:192
	global_load_dwordx4 v[134:137], v[12:13], off offset:192
	global_load_dwordx4 v[138:141], v[14:15], off offset:192
	s_waitcnt vmcnt(16)
	v_mfma_f32_16x16x32_bf16 v[46:49], v[142:145], v[158:161], v[46:49]
	v_mfma_f32_16x16x32_bf16 v[50:53], v[142:145], v[162:165], v[50:53]
	v_mfma_f32_16x16x32_bf16 v[54:57], v[142:145], v[166:169], v[54:57]
	v_mfma_f32_16x16x32_bf16 v[58:61], v[142:145], v[170:173], v[58:61]
	v_mfma_f32_16x16x32_bf16 v[62:65], v[146:149], v[158:161], v[62:65]
	v_mfma_f32_16x16x32_bf16 v[66:69], v[146:149], v[162:165], v[66:69]
	v_mfma_f32_16x16x32_bf16 v[70:73], v[146:149], v[166:169], v[70:73]
	v_mfma_f32_16x16x32_bf16 v[74:77], v[146:149], v[170:173], v[74:77]
	v_mfma_f32_16x16x32_bf16 v[78:81], v[150:153], v[158:161], v[78:81]
	v_mfma_f32_16x16x32_bf16 v[82:85], v[150:153], v[162:165], v[82:85]
	v_mfma_f32_16x16x32_bf16 v[86:89], v[150:153], v[166:169], v[86:89]
	v_mfma_f32_16x16x32_bf16 v[90:93], v[150:153], v[170:173], v[90:93]
	v_mfma_f32_16x16x32_bf16 v[94:97], v[154:157], v[158:161], v[94:97]
	v_mfma_f32_16x16x32_bf16 v[98:101], v[154:157], v[162:165], v[98:101]
	v_mfma_f32_16x16x32_bf16 v[102:105], v[154:157], v[166:169], v[102:105]
	v_mfma_f32_16x16x32_bf16 v[106:109], v[154:157], v[170:173], v[106:109]
	s_waitcnt vmcnt(8)
	v_mfma_f32_16x16x32_bf16 v[46:49], v[174:177], v[202:205], v[46:49]
	v_mfma_f32_16x16x32_bf16 v[50:53], v[174:177], v[206:209], v[50:53]
	v_mfma_f32_16x16x32_bf16 v[54:57], v[174:177], v[210:213], v[54:57]
	v_mfma_f32_16x16x32_bf16 v[58:61], v[174:177], v[214:217], v[58:61]
	v_mfma_f32_16x16x32_bf16 v[62:65], v[178:181], v[202:205], v[62:65]
	v_mfma_f32_16x16x32_bf16 v[66:69], v[178:181], v[206:209], v[66:69]
	v_mfma_f32_16x16x32_bf16 v[70:73], v[178:181], v[210:213], v[70:73]
	v_mfma_f32_16x16x32_bf16 v[74:77], v[178:181], v[214:217], v[74:77]
	v_mfma_f32_16x16x32_bf16 v[78:81], v[182:185], v[202:205], v[78:81]
	v_mfma_f32_16x16x32_bf16 v[82:85], v[182:185], v[206:209], v[82:85]
	v_mfma_f32_16x16x32_bf16 v[86:89], v[182:185], v[210:213], v[86:89]
	v_mfma_f32_16x16x32_bf16 v[90:93], v[182:185], v[214:217], v[90:93]
	v_mfma_f32_16x16x32_bf16 v[94:97], v[198:201], v[202:205], v[94:97]
	v_mfma_f32_16x16x32_bf16 v[98:101], v[198:201], v[206:209], v[98:101]
	v_mfma_f32_16x16x32_bf16 v[102:105], v[198:201], v[210:213], v[102:105]
	v_mfma_f32_16x16x32_bf16 v[106:109], v[198:201], v[214:217], v[106:109]
	s_waitcnt vmcnt(0)
; #define LAS __attribute__((address_space(3)))
; template <int NKS, bool ATILED = false, bool FFN = false, bool HALF = false, class EF> ...
;     ...
;         LAS float* part = lf + w * 4096;
; #pragma unroll
;         for (int mi = 0; mi < MI; ++mi)
; #pragma unroll
;             for (int ni = 0; ni < 4; ++ni)
; #pragma unroll
;                 for (int i = 0; i < 4; ++i) part[(16 * mi + 4 * kq + i) * 64 + 16 * ni + c16] = acc[mi][ni][i];
;         __syncthreads();
;         const int row = tid >> 3, c8 = (tid & 7) * 8; float v[8];
;         if (!HALF || tid < 256) {
; #pragma unroll
;         for (int i = 0; i < 8; ++i) v[i] = 0.f;
; #pragma unroll
;         for (int w2 = 0; w2 < 8; ++w2) { const f32x4 x = *(const LAS f32x4*)(lf + w2 * 4096 + row * 64 + c8), y = *(const LAS f32x4*)(lf + w2 * 4096 + row * 64 + c8 + 4);
;             v[0] += x[0]; v[1] += x[1]; v[2] += x[2]; v[3] += x[3]; v[4] += y[0]; v[5] += y[1]; v[6] += y[2]; v[7] += y[3]; }
;         }
;         if constexpr (FFN) ef.ffn(lf, 64 * rb + row, row, cb, c8, v);
;         else if (!HALF || tid < 256) ef(RB * rb + row, 64 * cb + c8, v, lane);
	v_mfma_f32_16x16x32_bf16 v[46:49], v[110:113], v[126:129], v[46:49]
	v_mfma_f32_16x16x32_bf16 v[50:53], v[110:113], v[130:133], v[50:53]
	v_mfma_f32_16x16x32_bf16 v[54:57], v[110:113], v[134:137], v[54:57]
	v_mfma_f32_16x16x32_bf16 v[58:61], v[110:113], v[138:141], v[58:61]
	v_mfma_f32_16x16x32_bf16 v[62:65], v[114:117], v[126:129], v[62:65]
	v_mfma_f32_16x16x32_bf16 v[66:69], v[114:117], v[130:133], v[66:69]
	v_mfma_f32_16x16x32_bf16 v[70:73], v[114:117], v[134:137], v[70:73]
	v_mfma_f32_16x16x32_bf16 v[74:77], v[114:117], v[138:141], v[74:77]
	v_mfma_f32_16x16x32_bf16 v[78:81], v[118:121], v[126:129], v[78:81]
	v_mfma_f32_16x16x32_bf16 v[82:85], v[118:121], v[130:133], v[82:85]
	v_mfma_f32_16x16x32_bf16 v[86:89], v[118:121], v[134:137], v[86:89]
	v_mfma_f32_16x16x32_bf16 v[90:93], v[118:121], v[138:141], v[90:93]
	v_mfma_f32_16x16x32_bf16 v[94:97], v[122:125], v[126:129], v[94:97]
	v_mfma_f32_16x16x32_bf16 v[98:101], v[122:125], v[130:133], v[98:101]
	v_mfma_f32_16x16x32_bf16 v[102:105], v[122:125], v[134:137], v[102:105]
	v_mfma_f32_16x16x32_bf16 v[106:109], v[122:125], v[138:141], v[106:109]
	s_nop 7
	ds_write2_b32 v30, v46, v50 offset1:16
	ds_write2_b32 v30, v47, v51 offset0:64 offset1:80
	ds_write2_b32 v30, v48, v52 offset0:128 offset1:144
	ds_write2_b32 v30, v49, v53 offset0:192 offset1:208
	ds_write2_b32 v30, v54, v58 offset0:32 offset1:48
	ds_write2_b32 v30, v55, v59 offset0:96 offset1:112
	ds_write2_b32 v30, v56, v60 offset0:160 offset1:176
	ds_write2_b32 v30, v57, v61 offset0:224 offset1:240
	ds_write2_b32 v41, v62, v66 offset1:16
	ds_write2_b32 v41, v63, v67 offset0:64 offset1:80
	ds_write2_b32 v41, v64, v68 offset0:128 offset1:144
	ds_write2_b32 v41, v65, v69 offset0:192 offset1:208
	ds_write2_b32 v41, v70, v74 offset0:32 offset1:48
	ds_write2_b32 v41, v71, v75 offset0:96 offset1:112
	ds_write2_b32 v41, v72, v76 offset0:160 offset1:176
	ds_write2_b32 v41, v73, v77 offset0:224 offset1:240
	ds_write2_b32 v42, v78, v82 offset1:16
	ds_write2_b32 v42, v79, v83 offset0:64 offset1:80
	ds_write2_b32 v42, v80, v84 offset0:128 offset1:144
	ds_write2_b32 v42, v81, v85 offset0:192 offset1:208
	ds_write2_b32 v42, v86, v90 offset0:32 offset1:48
	ds_write2_b32 v42, v87, v91 offset0:96 offset1:112
	ds_write2_b32 v42, v88, v92 offset0:160 offset1:176
	ds_write2_b32 v42, v89, v93 offset0:224 offset1:240
	ds_write2_b32 v43, v94, v98 offset1:16
	ds_write2_b32 v43, v95, v99 offset0:64 offset1:80
	ds_write2_b32 v43, v96, v100 offset0:128 offset1:144
	ds_write2_b32 v43, v97, v101 offset0:192 offset1:208
	ds_write2_b32 v43, v102, v106 offset0:32 offset1:48
	ds_write2_b32 v43, v103, v107 offset0:96 offset1:112
	ds_write2_b32 v43, v104, v108 offset0:160 offset1:176
	ds_write2_b32 v43, v105, v109 offset0:224 offset1:240
	s_waitcnt lgkmcnt(0)
	s_barrier
	ds_read_b128 v[2:5], v23
	ds_read_b128 v[6:9], v23 offset:16
	ds_read_b128 v[10:13], v23 offset:16384
	ds_read_b128 v[26:29], v23 offset:16400
	ds_read_b128 v[46:49], v23 offset:32768
	ds_read_b128 v[50:53], v23 offset:32784
	ds_read_b128 v[54:57], v23 offset:49152
	ds_read_b128 v[58:61], v23 offset:49168
	ds_read_b128 v[62:65], v31
	ds_read_b128 v[66:69], v32
	ds_read_b128 v[70:73], v33
	ds_read_b128 v[74:77], v34
	ds_read_b128 v[78:81], v35
	ds_read_b128 v[82:85], v36
	ds_read_b128 v[86:89], v37
	ds_read_b128 v[90:93], v38
	s_waitcnt lgkmcnt(14)
	v_pk_add_f32 v[2:3], v[2:3], 0 op_sel_hi:[1,0]
	v_pk_add_f32 v[4:5], v[4:5], 0 op_sel_hi:[1,0]
	v_pk_add_f32 v[6:7], v[6:7], 0 op_sel_hi:[1,0]
	v_pk_add_f32 v[8:9], v[8:9], 0 op_sel_hi:[1,0]
	s_waitcnt lgkmcnt(13)
	v_pk_add_f32 v[2:3], v[2:3], v[10:11]
	v_pk_add_f32 v[4:5], v[4:5], v[12:13]
	s_waitcnt lgkmcnt(12)
	v_pk_add_f32 v[6:7], v[6:7], v[26:27]
	v_pk_add_f32 v[8:9], v[8:9], v[28:29]
	s_waitcnt lgkmcnt(11)
	v_pk_add_f32 v[2:3], v[2:3], v[46:47]
	v_pk_add_f32 v[4:5], v[4:5], v[48:49]
	s_waitcnt lgkmcnt(10)
	v_pk_add_f32 v[6:7], v[6:7], v[50:51]
	v_pk_add_f32 v[8:9], v[8:9], v[52:53]
	s_waitcnt lgkmcnt(9)
	v_pk_add_f32 v[2:3], v[2:3], v[54:55]
	v_pk_add_f32 v[4:5], v[4:5], v[56:57]
	s_waitcnt lgkmcnt(8)
	v_pk_add_f32 v[6:7], v[6:7], v[58:59]
	v_pk_add_f32 v[8:9], v[8:9], v[60:61]
	s_waitcnt lgkmcnt(7)
	v_pk_add_f32 v[2:3], v[2:3], v[62:63]
	v_pk_add_f32 v[4:5], v[4:5], v[64:65]
	s_waitcnt lgkmcnt(6)
	v_pk_add_f32 v[6:7], v[6:7], v[66:67]
	v_pk_add_f32 v[8:9], v[8:9], v[68:69]
	v_or_b32_e32 v28, s0, v1
	s_waitcnt lgkmcnt(5)
	v_pk_add_f32 v[2:3], v[2:3], v[70:71]
	v_pk_add_f32 v[4:5], v[4:5], v[72:73]
	s_waitcnt lgkmcnt(4)
	v_pk_add_f32 v[6:7], v[6:7], v[74:75]
	v_pk_add_f32 v[8:9], v[8:9], v[76:77]
	v_ashrrev_i32_e32 v29, 31, v28
	s_mov_b64 s[0:1], 0x4000
	s_waitcnt lgkmcnt(3)
	v_pk_add_f32 v[2:3], v[2:3], v[78:79]
	v_pk_add_f32 v[4:5], v[4:5], v[80:81]
	s_waitcnt lgkmcnt(2)
	v_pk_add_f32 v[6:7], v[6:7], v[82:83]
	v_pk_add_f32 v[8:9], v[8:9], v[84:85]
	v_lshl_add_u64 v[12:13], v[28:29], 0, s[0:1]
	s_movk_i32 s0, 0x1ff
	s_waitcnt lgkmcnt(1)
	v_pk_add_f32 v[2:3], v[2:3], v[86:87]
	v_pk_add_f32 v[4:5], v[4:5], v[88:89]
	s_waitcnt lgkmcnt(0)
	v_pk_add_f32 v[6:7], v[6:7], v[90:91]
	v_pk_add_f32 v[8:9], v[8:9], v[92:93]
	v_cmp_lt_i32_e32 vcc, s0, v16
	s_and_saveexec_b64 s[0:1], vcc
	s_xor_b64 s[12:13], exec, s[0:1]
	s_cbranch_execz .LBB0_263
	s_mov_b64 s[0:1], -1
	s_cmpk_gt_u32 s30, 0x5ff
	v_lshlrev_b64 v[26:27], 10, v[12:13]
	s_cbranch_scc0 .LBB0_258
	v_lshl_add_u64 v[14:15], s[10:11], 0, v[26:27]
	v_add_u32_e32 v46, 0xfffffa00, v16
	v_mov_b32_e32 v47, v17
	v_cvt_pk_bf16_f32 v10, v2, v3
	v_cvt_pk_bf16_f32 v11, v4, v5
	v_cvt_pk_bf16_f32 v12, v6, v7
	v_cvt_pk_bf16_f32 v13, v8, v9
	v_lshl_add_u64 v[14:15], v[46:47], 1, v[14:15]
	global_store_dwordx4 v[14:15], v[10:13], off
	s_mov_b64 s[0:1], 0
	s_nop 0
	v_lshlrev_b64 v[10:11], 11, v[28:29]
	v_lshl_add_u64 v[10:11], s[2:3], 0, v[10:11]
	v_lshl_add_u64 v[10:11], v[46:47], 2, v[10:11]
	global_store_dwordx4 v[10:11], v[2:5], off
	global_store_dwordx4 v[10:11], v[6:9], off offset:16

; #define LAS __attribute__((address_space(3)))
; __device__ __forceinline__ float row_rs(const float* SS, int r) {
;     const f32x4* p = (const f32x4*)(SS + (size_t)r * 16); const f32x4 a = p[0], b = p[1], c = p[2], d = p[3];
;     const float s = ((a[0] + a[1]) + (a[2] + a[3])) + ((b[0] + b[1]) + (b[2] + b[3])) + ((c[0] + c[1]) + (c[2] + c[3])) + ((d[0] + d[1]) + (d[2] + d[3]));
;     return 1.f / sqrtf(s * (1.f / DMODEL) + EPS);
; }
; __device__ __forceinline__ void tile_rs(const float* SS, int pm, LAS float* rsl) {
;     const int tid = threadIdx.x;
;     if (tid < 256) rsl[tid] = row_rs(SS, pm * 256 + tid);
;     asm volatile("s_waitcnt lgkmcnt(0)" ::: "memory"); __builtin_amdgcn_s_barrier(); asm volatile("" ::: "memory");
; }
;     __device__ __forceinline__ void operator()(const f32x4 (&acc)[2][2][4][2], const Unit& u, int wr, int wc, int fr, int fq) const {
;     ...
;         for (int n = 0; n < 2; ++n) { w0[n] = *(const f32x4*)(cw_ + ch0 + 4 * n); w1[n] = *(const f32x4*)(cw_ + FF + ch0 + 4 * n); w2[n] = *(const f32x4*)(cw_ + 2 * FF + ch0 + 4 * n); bb[n] = *(const f32x4*)(cb_ + ch0 + 4 * n); }
.LBB0_1078:
	global_load_dwordx4 v[220:223], v[158:159], off
	global_load_dwordx4 v[224:227], v[164:165], off
	global_load_dwordx4 v[232:235], v[160:161], off
	global_load_dwordx4 v[236:239], v[162:163], off
	global_load_dwordx4 v[240:243], v[158:159], off offset:16
	global_load_dwordx4 v[244:247], v[160:161], off offset:16
	global_load_dwordx4 v[248:251], v[162:163], off offset:16
	s_add_i32 s31, s78, s26
	s_lshl_b32 s30, s31, 8
	s_and_saveexec_b64 s[28:29], s[4:5]
	s_cbranch_execz .LBB0_1080
	v_or_b32_e32 v66, s30, v0
	v_ashrrev_i32_e32 v67, 31, v66
	v_lshlrev_b64 v[66:67], 6, v[66:67]
	v_lshl_add_u64 v[170:171], s[14:15], 0, v[66:67]
	global_load_dwordx4 v[66:69], v[170:171], off
	global_load_dwordx4 v[70:73], v[170:171], off offset:16
	global_load_dwordx4 v[166:169], v[170:171], off offset:32
	s_nop 0
	global_load_dwordx4 v[170:173], v[170:171], off offset:48
	s_waitcnt vmcnt(0)
	v_mov_b32_e32 v174, v67
	v_mov_b32_e32 v175, v68
	v_mov_b32_e32 v67, v69
	v_mov_b32_e32 v68, v71
	v_mov_b32_e32 v69, v72
	v_mov_b32_e32 v71, v73
	v_pk_add_f32 v[66:67], v[174:175], v[66:67]
	v_pk_add_f32 v[68:69], v[68:69], v[70:71]
	v_pk_add_f32 v[66:67], v[66:67], v[66:67] op_sel:[0,1] op_sel_hi:[1,0]
	v_pk_add_f32 v[68:69], v[68:69], v[68:69] op_sel:[0,1] op_sel_hi:[1,0]
	v_add_f32_e32 v72, v166, v167
	v_add_f32_e32 v166, v168, v169
	v_mov_b32_e32 v73, v172
	v_mov_b32_e32 v167, v173
	v_mov_b32_e32 v67, v170
	v_mov_b32_e32 v69, v171
	v_pk_add_f32 v[70:71], v[72:73], v[166:167]
	v_pk_add_f32 v[66:67], v[66:67], v[68:69]
	s_nop 0
	v_pk_add_f32 v[66:67], v[66:67], v[70:71]
	s_nop 0
	v_add_f32_e32 v66, v66, v67
	v_fmamk_f32 v66, v66, 0x3a800000, v210
	v_mul_f32_e32 v67, 0x4f800000, v66
	v_cmp_gt_f32_e32 vcc, s59, v66
	s_nop 1
	v_cndmask_b32_e32 v66, v66, v67, vcc
	v_sqrt_f32_e32 v67, v66
	s_nop 0
	v_add_u32_e32 v68, -1, v67
	v_add_u32_e32 v69, 1, v67
	v_fma_f32 v70, -v68, v67, v66
	v_fma_f32 v71, -v69, v67, v66
	v_cmp_ge_f32_e64 s[0:1], 0, v70
	s_nop 1
	v_cndmask_b32_e64 v67, v67, v68, s[0:1]
	v_cmp_lt_f32_e64 s[0:1], 0, v71
	s_nop 1
	v_cndmask_b32_e64 v67, v67, v69, s[0:1]
	v_mul_f32_e32 v68, 0x37800000, v67
	v_cndmask_b32_e32 v67, v67, v68, vcc
	v_cmp_class_f32_e32 vcc, v66, v211
	s_nop 1
	v_cndmask_b32_e32 v66, v67, v66, vcc
	v_div_scale_f32 v67, s[0:1], v66, v66, 1.0
	v_rcp_f32_e32 v68, v67
	v_div_scale_f32 v69, vcc, 1.0, v66, 1.0
	v_fma_f32 v70, -v67, v68, 1.0
	v_fmac_f32_e32 v68, v70, v68
	v_mul_f32_e32 v70, v69, v68
	v_fma_f32 v71, -v67, v70, v69
	v_fmac_f32_e32 v70, v71, v68
	v_fma_f32 v67, -v67, v70, v69
	v_div_fmas_f32 v67, v67, v68, v70
	v_div_fixup_f32 v66, v67, v66, 1.0
	ds_write_b32 v206, v66

;     __device__ __forceinline__ void operator()(const f32x4 (&acc)[2][2][4][2], const Unit& u, int wr, int wc, int fr, int fq) const {
;     ...
;         tile_rs(SS, u.pm, rsl);
;         f32x4 gs[2][4][2];
; _Pragma("unroll")
;         for (int ai = 0; ai < 2; ++ai)
; _Pragma("unroll")
;             for (int m = 0; m < 4; ++m) { const float rs = rsl[128 * ai + 64 * wr + 16 * m + fr]; gs[ai][m][0] = acc[ai][0][m][0] * rs; gs[ai][m][1] = acc[ai][0][m][1] * rs; }
;         if (fr >= 14) {
;             const bool seq_end = (u.pm & 15) == 15;
; _Pragma("unroll")
;             for (int ai = 0; ai < 2; ++ai) { const int q = 2 * ai + wr + 1; const int slot = q < 4 ? q : 4 + ((u.pm + 1) & 1); const bool zero = (q == 4) && seq_end;
; _Pragma("unroll")
;                 for (int n = 0; n < 2; ++n) *(LAS f32x4*)(hal + halo_idx(slot, wc, fr - 14, ci0 + 4 * n)) = zero ? (f32x4){0.f, 0.f, 0.f, 0.f} : gs[ai][3][n];
;                 if (seq_end && ai == 1 && wr == 1) {
;                     float* co = out + O_CP + (size_t)((u.pm >> 4) * 2 + (fr - 14)) * FF + ch0; *(f32x4*)co = gs[1][3][0]; *(f32x4*)(co + 4) = gs[1][3][1]; } }
;         }
;         asm volatile("s_waitcnt lgkmcnt(0)" ::: "memory"); __builtin_amdgcn_s_barrier(); asm volatile("" ::: "memory");
;         f32x4 w0[2], w1[2], w2[2], bb[2];
; _Pragma("unroll")
;         for (int n = 0; n < 2; ++n) { w0[n] = *(const f32x4*)(cw_ + ch0 + 4 * n); w1[n] = *(const f32x4*)(cw_ + FF + ch0 + 4 * n); w2[n] = *(const f32x4*)(cw_ + 2 * FF + ch0 + 4 * n); bb[n] = *(const f32x4*)(cb_ + ch0 + 4 * n); }
; _Pragma("unroll")
;         for (int ai = 0; ai < 2; ++ai)
; _Pragma("unroll")
;             for (int m = 0; m < 4; ++m) { const int r = row0 + 128 * ai + 16 * m; const float rs = rsl[128 * ai + 64 * wr + 16 * m + fr]; f32x4 o[2];
; _Pragma("unroll")
;                 for (int n = 0; n < 2; ++n) { f32x4 p1, p2, q1, q2;
;                     if (m > 0) {
; _Pragma("unroll")
;                         for (int j = 0; j < 4; ++j) { q1[j] = row_from_below<1>(gs[ai][m - 1][n][j]); q2[j] = row_from_below<2>(gs[ai][m - 1][n][j]); } }
;                     else { const int slot = (2 * ai + wr) ? (2 * ai + wr) : 4 + (u.pm & 1);
;                         q1 = *(const LAS f32x4*)(hal + halo_idx(slot, wc, 1, ci0 + 4 * n)); q2 = *(const LAS f32x4*)(hal + halo_idx(slot, wc, fr == 0 ? 0 : 1, ci0 + 4 * n)); }
; _Pragma("unroll")
.LBB0_1086:
	s_or_b64 exec, exec, s[0:1]
	s_waitcnt lgkmcnt(0)
	s_barrier
	s_waitcnt vmcnt(0)
	v_mov_b32_e32 v58, v220
	v_mov_b32_e32 v59, v221
	v_mov_b32_e32 v60, v222
	v_mov_b32_e32 v61, v223
	v_mov_b32_e32 v70, v224
	v_mov_b32_e32 v71, v225
	v_mov_b32_e32 v72, v226
	v_mov_b32_e32 v73, v227
	v_mov_b32_e32 v62, v232
	v_mov_b32_e32 v63, v233
	v_mov_b32_e32 v64, v234
	v_mov_b32_e32 v65, v235
	v_mov_b32_e32 v66, v236
	v_mov_b32_e32 v67, v237
	v_mov_b32_e32 v68, v238
	v_mov_b32_e32 v69, v239
	v_pk_mul_f32 v[166:167], v[44:45], v[172:173] op_sel_hi:[1,0]
	v_pk_mul_f32 v[168:169], v[42:43], v[172:173] op_sel_hi:[1,0]
	v_pk_mul_f32 v[170:171], v[48:49], v[172:173] op_sel_hi:[1,0]
	v_pk_mul_f32 v[172:173], v[46:47], v[172:173] op_sel_hi:[1,0]
	v_mov_b32_e32 v218, v185
	v_pk_mul_f32 v[174:175], v[52:53], v[184:185] op_sel_hi:[1,0]
	v_pk_mul_f32 v[176:177], v[50:51], v[184:185] op_sel_hi:[1,0]
	v_pk_mul_f32 v[182:183], v[56:57], v[184:185] op_sel_hi:[1,0]
	v_pk_mul_f32 v[184:185], v[54:55], v[184:185] op_sel_hi:[1,0]
	v_mov_b32_e32 v42, v240
	v_mov_b32_e32 v43, v241
	v_mov_b32_e32 v44, v242
	v_mov_b32_e32 v45, v243
	v_mov_b32_e32 v46, v244
	v_mov_b32_e32 v47, v245
	v_mov_b32_e32 v48, v246
	v_mov_b32_e32 v49, v247
	v_mov_b32_e32 v50, v248
	v_mov_b32_e32 v51, v249
	v_mov_b32_e32 v52, v250
	v_mov_b32_e32 v53, v251
	global_load_dwordx4 v[54:57], v[164:165], off offset:16
	v_pk_mul_f32 v[190:191], v[122:123], v[194:195] op_sel_hi:[1,0]
	v_pk_mul_f32 v[230:231], v[134:135], v[192:193] op_sel_hi:[1,0]
	v_or_b32_e32 v123, 4, v195
	v_mov_b32_e32 v134, s64
	v_cndmask_b32_e64 v123, v134, v123, s[12:13]
	v_lshl_or_b32 v123, v123, 3, s72
	v_pk_mul_f32 v[132:133], v[132:133], v[192:193] op_sel_hi:[1,0]
	v_pk_mul_f32 v[226:227], v[130:131], v[192:193] op_sel_hi:[1,0]
	v_pk_mul_f32 v[228:229], v[136:137], v[192:193] op_sel_hi:[1,0]
	v_or_b32_e32 v192, v123, v203
	v_pk_mul_f32 v[124:125], v[124:125], v[194:195] op_sel_hi:[1,0]
	v_pk_mul_f32 v[128:129], v[128:129], v[194:195] op_sel_hi:[1,0]
	v_pk_mul_f32 v[126:127], v[126:127], v[194:195] op_sel_hi:[1,0]
	v_mov_b32_e32 v194, v193
	v_lshl_add_u32 v123, v123, 7, v204
	v_lshl_add_u32 v222, v192, 7, v204
	v_pk_mul_f32 v[108:109], v[108:109], v[218:219] op_sel_hi:[1,0]
	v_pk_mul_f32 v[106:107], v[106:107], v[218:219] op_sel_hi:[1,0]
	v_pk_mul_f32 v[112:113], v[112:113], v[218:219] op_sel_hi:[1,0]
	v_pk_mul_f32 v[110:111], v[110:111], v[218:219] op_sel_hi:[1,0]
	v_pk_mul_f32 v[116:117], v[116:117], v[194:195] op_sel_hi:[1,0]
	v_pk_mul_f32 v[114:115], v[114:115], v[194:195] op_sel_hi:[1,0]
	v_pk_mul_f32 v[120:121], v[120:121], v[194:195] op_sel_hi:[1,0]
	v_pk_mul_f32 v[130:131], v[118:119], v[194:195] op_sel_hi:[1,0]
	ds_read2_b32 v[118:119], v214 offset1:16
	ds_read_b128 v[134:137], v123 offset:128
	ds_read_b128 v[192:195], v123 offset:144
	ds_read_b128 v[218:221], v222
	ds_read_b128 v[222:225], v222 offset:16
	v_mov_b32_e32 v233, 0
	v_mov_b32_e32 v235, 0
	v_mov_b32_e32 v232, 0
	v_mov_b32_e32 v234, 0
	v_mov_b32_dpp v233, v230 row_ror:2 row_mask:0xf bank_mask:0xf
	v_mov_b32_dpp v235, v231 row_ror:2 row_mask:0xf bank_mask:0xf
	v_mov_b32_dpp v232, v230 row_ror:1 row_mask:0xf bank_mask:0xf
	v_mov_b32_dpp v234, v231 row_ror:1 row_mask:0xf bank_mask:0xf
	s_waitcnt lgkmcnt(0)
	v_cndmask_b32_e64 v219, v219, v235, s[10:11]
	v_cndmask_b32_e64 v218, v218, v233, s[10:11]
	v_cndmask_b32_e64 v135, v234, v135, s[8:9]
	v_cndmask_b32_e64 v134, v232, v134, s[8:9]
	v_mov_b32_e32 v237, 0
	v_mov_b32_e32 v239, 0
	v_mov_b32_e32 v236, 0
	v_mov_b32_e32 v238, 0
	v_mov_b32_dpp v237, v228 row_ror:2 row_mask:0xf bank_mask:0xf
	v_mov_b32_dpp v239, v229 row_ror:2 row_mask:0xf bank_mask:0xf
	v_mov_b32_dpp v236, v228 row_ror:1 row_mask:0xf bank_mask:0xf
	v_mov_b32_dpp v238, v229 row_ror:1 row_mask:0xf bank_mask:0xf
	v_cndmask_b32_e64 v221, v221, v239, s[10:11]
	v_cndmask_b32_e64 v220, v220, v237, s[10:11]
	v_cndmask_b32_e64 v137, v238, v137, s[8:9]
	v_cndmask_b32_e64 v136, v236, v136, s[8:9]
	v_pk_mul_f32 v[102:103], v[102:103], v[118:119] op_sel_hi:[1,0]
	v_pk_mul_f32 v[104:105], v[104:105], v[118:119] op_sel_hi:[1,0]
	v_pk_mul_f32 v[98:99], v[98:99], v[118:119] op_sel_hi:[1,0]
	v_add_u32_e32 v122, s30, v212
	v_pk_mul_f32 v[100:101], v[100:101], v[118:119] op_sel_hi:[1,0]
	v_mov_b32_e32 v118, 0
	s_cmp_eq_u32 s78, s75
	s_waitcnt vmcnt(0)
; #define LAS __attribute__((address_space(3)))
; __device__ __forceinline__ size_t hidx(size_t r, int c) { return ((size_t)(c >> 6) * MTOT + r) * 64 + (c & 63); }
; __device__ __forceinline__ u32x4 pack8(const f32x4 a, const f32x4 b) { u32x4 w; w.x = cvt_pk_bf16(a[0], a[1]); w.y = cvt_pk_bf16(a[2], a[3]); w.z = cvt_pk_bf16(b[0], b[1]); w.w = cvt_pk_bf16(b[2], b[3]); return w; }
; __device__ __forceinline__ float sigm(float x) { return 1.f / (1.f + __builtin_amdgcn_exp2f(-LOG2E * x)); }
; __device__ __forceinline__ int halo_idx(int slot, int wc, int row, int ci) { return ((slot * 4 + wc) * 2 + row) * 32 + ci; }
;     __device__ __forceinline__ void operator()(const f32x4 (&acc)[2][2][4][2], const Unit& u, int wr, int wc, int fr, int fq) const {
;     ...
;             for (int m = 0; m < 4; ++m) { const int r = row0 + 128 * ai + 16 * m; const float rs = rsl[128 * ai + 64 * wr + 16 * m + fr]; f32x4 o[2];
; _Pragma("unroll")
;                 for (int n = 0; n < 2; ++n) { f32x4 p1, p2, q1, q2;
;                     if (m > 0) {
; _Pragma("unroll")
;                         for (int j = 0; j < 4; ++j) { q1[j] = row_from_below<1>(gs[ai][m - 1][n][j]); q2[j] = row_from_below<2>(gs[ai][m - 1][n][j]); } }
;                     else { const int slot = (2 * ai + wr) ? (2 * ai + wr) : 4 + (u.pm & 1);
;                         q1 = *(const LAS f32x4*)(hal + halo_idx(slot, wc, 1, ci0 + 4 * n)); q2 = *(const LAS f32x4*)(hal + halo_idx(slot, wc, fr == 0 ? 0 : 1, ci0 + 4 * n)); }
; _Pragma("unroll")
;                     for (int j = 0; j < 4; ++j) { p1[j] = row_from_below<1>(gs[ai][m][n][j]); p2[j] = row_from_below<2>(gs[ai][m][n][j]); }
;                     const f32x4 h1 = fr >= 1 ? p1 : q1, h0 = fr >= 2 ? p2 : q2;
;                     const f32x4 cv = bb[n] + w0[n] * h0 + w1[n] * h1 + w2[n] * gs[ai][m][n];
; _Pragma("unroll")
;                     for (int j = 0; j < 4; ++j) o[n][j] = cv[j] * sigm(cv[j]) * (acc[ai][1][m][n][j] * rs); }
;                 *(u32x4*)(H + hidx(r, ch0)) = pack8(o[0], o[1]); }
	v_pk_fma_f32 v[218:219], v[58:59], v[218:219], v[70:71]
	s_nop 0
	v_pk_fma_f32 v[134:135], v[62:63], v[134:135], v[218:219]
	v_pk_fma_f32 v[220:221], v[60:61], v[220:221], v[72:73]
	v_pk_fma_f32 v[134:135], v[230:231], v[66:67], v[134:135]
	v_pk_fma_f32 v[136:137], v[64:65], v[136:137], v[220:221]
	v_mul_f32_e32 v123, 0xbfb8aa3b, v134
	v_mul_f32_e32 v219, 0xbfb8aa3b, v135
	v_exp_f32_e32 v218, v123
	v_exp_f32_e32 v219, v219
	v_pk_fma_f32 v[136:137], v[228:229], v[68:69], v[136:137]
	v_mov_b32_dpp v118, v130 row_ror:1 row_mask:0xf bank_mask:0xf
	v_pk_add_f32 v[218:219], v[218:219], 1.0 op_sel_hi:[1,0]
	s_nop 0
	v_rcp_f32_e32 v219, v219
	v_mul_f32_e32 v220, 0xbfb8aa3b, v136
	v_mul_f32_e32 v221, 0xbfb8aa3b, v137
	v_exp_f32_e32 v220, v220
	v_exp_f32_e32 v221, v221
	v_rcp_f32_e32 v218, v218
	s_nop 0
	v_pk_mul_f32 v[134:135], v[134:135], v[218:219]
	v_pk_add_f32 v[220:221], v[220:221], 1.0 op_sel_hi:[1,0]
	v_pk_mul_f32 v[102:103], v[102:103], v[134:135]
	v_mov_b32_e32 v229, 0
	v_mov_b32_e32 v230, 0
	v_mov_b32_e32 v231, 0
	v_rcp_f32_e32 v135, v221
	v_mov_b32_e32 v228, 0
	v_rcp_f32_e32 v134, v220
	v_mov_b32_e32 v218, 0
	v_mov_b32_e32 v219, 0
	v_mov_b32_e32 v220, 0
	v_mov_b32_e32 v221, 0
	v_mov_b32_dpp v218, v226 row_ror:1 row_mask:0xf bank_mask:0xf
	v_mov_b32_dpp v219, v226 row_ror:2 row_mask:0xf bank_mask:0xf
	v_mov_b32_dpp v220, v227 row_ror:1 row_mask:0xf bank_mask:0xf
	v_mov_b32_dpp v221, v227 row_ror:2 row_mask:0xf bank_mask:0xf
	v_pk_mul_f32 v[134:135], v[136:137], v[134:135]
	v_cndmask_b32_e64 v137, v220, v193, s[8:9]
	v_cndmask_b32_e64 v136, v218, v192, s[8:9]
	v_cndmask_b32_e64 v193, v223, v221, s[10:11]
	v_cndmask_b32_e64 v192, v222, v219, s[10:11]
	v_pk_fma_f32 v[192:193], v[42:43], v[192:193], v[54:55]
	v_mov_b32_dpp v228, v132 row_ror:1 row_mask:0xf bank_mask:0xf
	v_pk_fma_f32 v[136:137], v[46:47], v[136:137], v[192:193]
	v_mov_b32_dpp v229, v132 row_ror:2 row_mask:0xf bank_mask:0xf
	v_pk_fma_f32 v[136:137], v[226:227], v[50:51], v[136:137]
	v_mov_b32_dpp v230, v133 row_ror:1 row_mask:0xf bank_mask:0xf
	v_mul_f32_e32 v123, 0xbfb8aa3b, v136
	v_exp_f32_e32 v192, v123
	v_mul_f32_e32 v123, 0xbfb8aa3b, v137
	v_exp_f32_e32 v193, v123
	v_mov_b32_dpp v231, v133 row_ror:2 row_mask:0xf bank_mask:0xf
	v_pk_mul_f32 v[104:105], v[104:105], v[134:135]
	v_cndmask_b32_e64 v135, v230, v195, s[8:9]
	v_pk_add_f32 v[192:193], v[192:193], 1.0 op_sel_hi:[1,0]
	v_cndmask_b32_e64 v134, v228, v194, s[8:9]
	v_cndmask_b32_e64 v195, v225, v231, s[10:11]
	v_cndmask_b32_e64 v194, v224, v229, s[10:11]
	v_pk_fma_f32 v[194:195], v[44:45], v[194:195], v[56:57]
	s_nop 0
	v_pk_fma_f32 v[134:135], v[48:49], v[134:135], v[194:195]
	s_nop 0
	v_pk_fma_f32 v[132:133], v[132:133], v[52:53], v[134:135]
	v_rcp_f32_e32 v135, v193
	v_mul_f32_e32 v134, 0xbfb8aa3b, v132
	v_exp_f32_e32 v194, v134
	v_mul_f32_e32 v134, 0xbfb8aa3b, v133
	v_exp_f32_e32 v195, v134
	v_rcp_f32_e32 v134, v192
	s_nop 0
	v_pk_mul_f32 v[134:135], v[136:137], v[134:135]
	v_pk_add_f32 v[192:193], v[194:195], 1.0 op_sel_hi:[1,0]
	v_pk_mul_f32 v[134:135], v[98:99], v[134:135]
	s_nop 0
	v_rcp_f32_e32 v99, v193
	v_rcp_f32_e32 v98, v192
	s_nop 0
	v_pk_mul_f32 v[98:99], v[132:133], v[98:99]
	v_ashrrev_i32_e32 v123, 31, v122
	v_pk_mul_f32 v[132:133], v[100:101], v[98:99]
	v_cvt_pk_bf16_f32 v98, v102, v103
	v_lshl_add_u64 v[102:103], s[48:49], 0, v[122:123]
	v_cvt_pk_bf16_f32 v101, v132, v133
	v_lshlrev_b64 v[102:103], 7, v[102:103]
	v_mov_b32_e32 v123, 0
	v_mov_b32_e32 v133, 0
	v_cvt_pk_bf16_f32 v99, v104, v105
	v_cvt_pk_bf16_f32 v100, v134, v135
	v_lshl_add_u64 v[102:103], v[156:157], 0, v[102:103]
	v_mov_b32_dpp v123, v130 row_ror:2 row_mask:0xf bank_mask:0xf
	v_mov_b32_e32 v132, 0
	v_mov_b32_dpp v133, v131 row_ror:2 row_mask:0xf bank_mask:0xf
	global_store_dwordx4 v[102:103], v[98:101], off
	v_mov_b32_dpp v132, v131 row_ror:1 row_mask:0xf bank_mask:0xf
	v_cndmask_b32_e64 v103, v235, v133, s[10:11]
	v_cndmask_b32_e64 v102, v233, v123, s[10:11]
	v_cndmask_b32_e64 v101, v132, v234, s[8:9]
	v_cndmask_b32_e64 v100, v118, v232, s[8:9]
	v_pk_fma_f32 v[102:103], v[58:59], v[102:103], v[70:71]
	v_mov_b32_e32 v135, 0
	v_pk_fma_f32 v[100:101], v[62:63], v[100:101], v[102:103]
	v_mov_b32_e32 v137, 0
	v_pk_fma_f32 v[100:101], v[130:131], v[66:67], v[100:101]
	v_mov_b32_e32 v134, 0
	v_mul_f32_e32 v98, 0xbfb8aa3b, v100
	v_exp_f32_e32 v102, v98
	v_mul_f32_e32 v98, 0xbfb8aa3b, v101
	v_exp_f32_e32 v103, v98
	v_mov_b32_dpp v135, v120 row_ror:2 row_mask:0xf bank_mask:0xf
	v_mov_b32_e32 v136, 0
	v_mov_b32_dpp v137, v121 row_ror:2 row_mask:0xf bank_mask:0xf
	v_pk_add_f32 v[102:103], v[102:103], 1.0 op_sel_hi:[1,0]
	v_mov_b32_dpp v134, v120 row_ror:1 row_mask:0xf bank_mask:0xf
	v_mov_b32_dpp v136, v121 row_ror:1 row_mask:0xf bank_mask:0xf
	v_cndmask_b32_e64 v105, v239, v137, s[10:11]
	v_cndmask_b32_e64 v104, v237, v135, s[10:11]
	v_cndmask_b32_e64 v99, v136, v238, s[8:9]
	v_cndmask_b32_e64 v98, v134, v236, s[8:9]
	v_pk_fma_f32 v[104:105], v[60:61], v[104:105], v[72:73]
	v_mov_b32_e32 v193, 0
	v_pk_fma_f32 v[98:99], v[64:65], v[98:99], v[104:105]
	s_nop 0
	v_pk_fma_f32 v[98:99], v[120:121], v[68:69], v[98:99]
	v_rcp_f32_e32 v103, v103
	v_mul_f32_e32 v104, 0xbfb8aa3b, v98
	v_mul_f32_e32 v105, 0xbfb8aa3b, v99
	v_exp_f32_e32 v104, v104
	v_exp_f32_e32 v105, v105
	v_rcp_f32_e32 v102, v102
	s_nop 0
	v_pk_mul_f32 v[100:101], v[100:101], v[102:103]
	v_pk_add_f32 v[102:103], v[104:105], 1.0 op_sel_hi:[1,0]
	v_mov_b32_e32 v104, v119
	v_div_scale_f32 v105, s[0:1], v103, v103, 1.0
	v_rcp_f32_e32 v120, v105
	v_pk_mul_f32 v[94:95], v[94:95], v[104:105] op_sel_hi:[1,0]
	v_mov_b32_e32 v121, 0
	v_pk_mul_f32 v[94:95], v[94:95], v[100:101]
; #define LAS __attribute__((address_space(3)))
; __device__ __forceinline__ size_t hidx(size_t r, int c) { return ((size_t)(c >> 6) * MTOT + r) * 64 + (c & 63); }
; __device__ __forceinline__ u32x4 pack8(const f32x4 a, const f32x4 b) { u32x4 w; w.x = cvt_pk_bf16(a[0], a[1]); w.y = cvt_pk_bf16(a[2], a[3]); w.z = cvt_pk_bf16(b[0], b[1]); w.w = cvt_pk_bf16(b[2], b[3]); return w; }
; __device__ __forceinline__ float sigm(float x) { return 1.f / (1.f + __builtin_amdgcn_exp2f(-LOG2E * x)); }
; __device__ __forceinline__ int halo_idx(int slot, int wc, int row, int ci) { return ((slot * 4 + wc) * 2 + row) * 32 + ci; }
;     __device__ __forceinline__ void operator()(const f32x4 (&acc)[2][2][4][2], const Unit& u, int wr, int wc, int fr, int fq) const {
;     ...
;             for (int m = 0; m < 4; ++m) { const int r = row0 + 128 * ai + 16 * m; const float rs = rsl[128 * ai + 64 * wr + 16 * m + fr]; f32x4 o[2];
; _Pragma("unroll")
;                 for (int n = 0; n < 2; ++n) { f32x4 p1, p2, q1, q2;
;                     if (m > 0) {
; _Pragma("unroll")
;                         for (int j = 0; j < 4; ++j) { q1[j] = row_from_below<1>(gs[ai][m - 1][n][j]); q2[j] = row_from_below<2>(gs[ai][m - 1][n][j]); } }
;                     else { const int slot = (2 * ai + wr) ? (2 * ai + wr) : 4 + (u.pm & 1);
;                         q1 = *(const LAS f32x4*)(hal + halo_idx(slot, wc, 1, ci0 + 4 * n)); q2 = *(const LAS f32x4*)(hal + halo_idx(slot, wc, fr == 0 ? 0 : 1, ci0 + 4 * n)); }
; _Pragma("unroll")
;                     for (int j = 0; j < 4; ++j) { p1[j] = row_from_below<1>(gs[ai][m][n][j]); p2[j] = row_from_below<2>(gs[ai][m][n][j]); }
;                     const f32x4 h1 = fr >= 1 ? p1 : q1, h0 = fr >= 2 ? p2 : q2;
;                     const f32x4 cv = bb[n] + w0[n] * h0 + w1[n] * h1 + w2[n] * gs[ai][m][n];
; _Pragma("unroll")
;                     for (int j = 0; j < 4; ++j) o[n][j] = cv[j] * sigm(cv[j]) * (acc[ai][1][m][n][j] * rs); }
;                 *(u32x4*)(H + hidx(r, ch0)) = pack8(o[0], o[1]); }
	v_fma_f32 v100, -v105, v120, 1.0
	v_fmac_f32_e32 v120, v100, v120
	v_div_scale_f32 v100, vcc, 1.0, v103, 1.0
	v_mul_f32_e32 v101, v100, v120
	v_fma_f32 v119, -v105, v101, v100
	v_fmac_f32_e32 v101, v119, v120
	v_fma_f32 v100, -v105, v101, v100
	v_div_scale_f32 v105, s[0:1], v102, v102, 1.0
	v_rcp_f32_e32 v119, v105
	v_div_fmas_f32 v100, v100, v120, v101
	v_div_fixup_f32 v101, v100, v103, 1.0
	v_pk_mul_f32 v[96:97], v[96:97], v[104:105] op_sel_hi:[1,0]
	v_fma_f32 v100, -v105, v119, 1.0
	v_fmac_f32_e32 v119, v100, v119
	v_div_scale_f32 v100, vcc, 1.0, v102, 1.0
	v_mul_f32_e32 v103, v100, v119
	v_fma_f32 v120, -v105, v103, v100
	v_fmac_f32_e32 v103, v120, v119
	v_fma_f32 v100, -v105, v103, v100
	v_div_fmas_f32 v100, v100, v119, v103
	v_mov_b32_e32 v119, 0
	v_mov_b32_e32 v105, 0
	v_mov_b32_e32 v120, 0
	v_mov_b32_dpp v119, v114 row_ror:2 row_mask:0xf bank_mask:0xf
	v_mov_b32_dpp v121, v115 row_ror:2 row_mask:0xf bank_mask:0xf
	v_div_fixup_f32 v100, v100, v102, 1.0
	v_mov_b32_dpp v105, v114 row_ror:1 row_mask:0xf bank_mask:0xf
	v_mov_b32_dpp v120, v115 row_ror:1 row_mask:0xf bank_mask:0xf
	v_cndmask_b32_e64 v103, v221, v121, s[10:11]
	v_cndmask_b32_e64 v102, v219, v119, s[10:11]
	v_pk_mul_f32 v[98:99], v[98:99], v[100:101]
	v_cndmask_b32_e64 v101, v120, v220, s[8:9]
	v_cndmask_b32_e64 v100, v105, v218, s[8:9]
	v_pk_fma_f32 v[102:103], v[42:43], v[102:103], v[54:55]
	v_pk_mul_f32 v[96:97], v[96:97], v[98:99]
	v_pk_fma_f32 v[100:101], v[46:47], v[100:101], v[102:103]
	v_mov_b32_e32 v131, 0
	v_pk_fma_f32 v[100:101], v[114:115], v[50:51], v[100:101]
	v_mov_b32_e32 v130, 0
	v_mul_f32_e32 v98, 0xbfb8aa3b, v100
	v_exp_f32_e32 v102, v98
	v_mul_f32_e32 v98, 0xbfb8aa3b, v101
	v_exp_f32_e32 v103, v98
	v_mov_b32_dpp v131, v116 row_ror:2 row_mask:0xf bank_mask:0xf
	v_mov_b32_e32 v192, 0
	v_mov_b32_dpp v193, v117 row_ror:2 row_mask:0xf bank_mask:0xf
	v_pk_add_f32 v[102:103], v[102:103], 1.0 op_sel_hi:[1,0]
	v_mov_b32_dpp v130, v116 row_ror:1 row_mask:0xf bank_mask:0xf
	v_mov_b32_dpp v192, v117 row_ror:1 row_mask:0xf bank_mask:0xf
	v_cndmask_b32_e64 v115, v231, v193, s[10:11]
	v_cndmask_b32_e64 v114, v229, v131, s[10:11]
	v_cndmask_b32_e64 v99, v192, v230, s[8:9]
	v_cndmask_b32_e64 v98, v130, v228, s[8:9]
	v_pk_fma_f32 v[114:115], v[44:45], v[114:115], v[56:57]
	v_pk_mul_f32 v[90:91], v[90:91], v[104:105] op_sel_hi:[1,0]
	v_pk_fma_f32 v[98:99], v[48:49], v[98:99], v[114:115]
	s_nop 0
	v_pk_fma_f32 v[98:99], v[116:117], v[52:53], v[98:99]
	v_rcp_f32_e32 v103, v103
	v_mul_f32_e32 v114, 0xbfb8aa3b, v98
	v_mul_f32_e32 v115, 0xbfb8aa3b, v99
	v_exp_f32_e32 v114, v114
	v_exp_f32_e32 v115, v115
	v_rcp_f32_e32 v102, v102
	s_nop 0
	v_pk_mul_f32 v[100:101], v[100:101], v[102:103]
	v_pk_add_f32 v[114:115], v[114:115], 1.0 op_sel_hi:[1,0]
	v_pk_mul_f32 v[100:101], v[90:91], v[100:101]
	v_pk_mul_f32 v[92:93], v[92:93], v[104:105] op_sel_hi:[1,0]
	v_mov_b32_e32 v104, 0
	v_rcp_f32_e32 v91, v115
	v_rcp_f32_e32 v90, v114
	v_or_b32_e32 v102, 16, v122
	v_pk_mul_f32 v[90:91], v[98:99], v[90:91]
	v_ashrrev_i32_e32 v103, 31, v102
	v_pk_mul_f32 v[98:99], v[92:93], v[90:91]
	v_cvt_pk_bf16_f32 v90, v94, v95
	v_cvt_pk_bf16_f32 v92, v100, v101
	v_lshl_add_u64 v[94:95], s[48:49], 0, v[102:103]
	v_mov_b32_e32 v101, 0
	v_mov_b32_e32 v103, 0
	v_lshlrev_b64 v[94:95], 7, v[94:95]
	v_mov_b32_e32 v100, 0
	v_mov_b32_dpp v101, v126 row_ror:2 row_mask:0xf bank_mask:0xf
	v_mov_b32_e32 v102, 0
	v_mov_b32_dpp v103, v127 row_ror:2 row_mask:0xf bank_mask:0xf
	v_cvt_pk_bf16_f32 v91, v96, v97
	v_cvt_pk_bf16_f32 v93, v98, v99
	v_lshl_add_u64 v[94:95], v[156:157], 0, v[94:95]
	v_mov_b32_dpp v100, v126 row_ror:1 row_mask:0xf bank_mask:0xf
	v_mov_b32_dpp v102, v127 row_ror:1 row_mask:0xf bank_mask:0xf
	v_cndmask_b32_e64 v97, v133, v103, s[10:11]
	v_cndmask_b32_e64 v96, v123, v101, s[10:11]
	global_store_dwordx4 v[94:95], v[90:93], off
	v_cndmask_b32_e64 v95, v102, v132, s[8:9]
	v_cndmask_b32_e64 v94, v100, v118, s[8:9]
	v_pk_fma_f32 v[96:97], v[58:59], v[96:97], v[70:71]
	v_mov_b32_e32 v114, 0
	v_pk_fma_f32 v[94:95], v[62:63], v[94:95], v[96:97]
	v_mov_b32_e32 v116, 0
	v_pk_fma_f32 v[94:95], v[126:127], v[66:67], v[94:95]
	v_mov_b32_dpp v114, v128 row_ror:2 row_mask:0xf bank_mask:0xf
	v_mul_f32_e32 v92, 0xbfb8aa3b, v94
	v_exp_f32_e32 v96, v92
	v_mul_f32_e32 v92, 0xbfb8aa3b, v95
	v_exp_f32_e32 v97, v92
	v_mov_b32_e32 v115, 0
	v_mov_b32_dpp v116, v129 row_ror:2 row_mask:0xf bank_mask:0xf
	v_mov_b32_dpp v104, v128 row_ror:1 row_mask:0xf bank_mask:0xf
	v_pk_add_f32 v[96:97], v[96:97], 1.0 op_sel_hi:[1,0]
	v_mov_b32_dpp v115, v129 row_ror:1 row_mask:0xf bank_mask:0xf
	v_cndmask_b32_e64 v99, v137, v116, s[10:11]
	v_cndmask_b32_e64 v98, v135, v114, s[10:11]
	v_cndmask_b32_e64 v93, v115, v136, s[8:9]
	v_cndmask_b32_e64 v92, v104, v134, s[8:9]
	v_pk_fma_f32 v[98:99], v[60:61], v[98:99], v[72:73]
	ds_read2_b32 v[90:91], v214 offset0:32 offset1:48
	v_pk_fma_f32 v[92:93], v[64:65], v[92:93], v[98:99]
	v_rcp_f32_e32 v97, v97
	v_pk_fma_f32 v[92:93], v[128:129], v[68:69], v[92:93]
	s_nop 0
	v_mul_f32_e32 v98, 0xbfb8aa3b, v92
	v_mul_f32_e32 v99, 0xbfb8aa3b, v93
	v_exp_f32_e32 v98, v98
	v_exp_f32_e32 v99, v99
	v_rcp_f32_e32 v96, v96
	s_nop 0
	v_pk_mul_f32 v[94:95], v[94:95], v[96:97]
	v_pk_add_f32 v[98:99], v[98:99], 1.0 op_sel_hi:[1,0]
	s_waitcnt lgkmcnt(0)
; #define LAS __attribute__((address_space(3)))
; __device__ __forceinline__ size_t hidx(size_t r, int c) { return ((size_t)(c >> 6) * MTOT + r) * 64 + (c & 63); }
; __device__ __forceinline__ u32x4 pack8(const f32x4 a, const f32x4 b) { u32x4 w; w.x = cvt_pk_bf16(a[0], a[1]); w.y = cvt_pk_bf16(a[2], a[3]); w.z = cvt_pk_bf16(b[0], b[1]); w.w = cvt_pk_bf16(b[2], b[3]); return w; }
; __device__ __forceinline__ float sigm(float x) { return 1.f / (1.f + __builtin_amdgcn_exp2f(-LOG2E * x)); }
; __device__ __forceinline__ int halo_idx(int slot, int wc, int row, int ci) { return ((slot * 4 + wc) * 2 + row) * 32 + ci; }
;     __device__ __forceinline__ void operator()(const f32x4 (&acc)[2][2][4][2], const Unit& u, int wr, int wc, int fr, int fq) const {
;     ...
;             for (int m = 0; m < 4; ++m) { const int r = row0 + 128 * ai + 16 * m; const float rs = rsl[128 * ai + 64 * wr + 16 * m + fr]; f32x4 o[2];
; _Pragma("unroll")
;                 for (int n = 0; n < 2; ++n) { f32x4 p1, p2, q1, q2;
;                     if (m > 0) {
; _Pragma("unroll")
;                         for (int j = 0; j < 4; ++j) { q1[j] = row_from_below<1>(gs[ai][m - 1][n][j]); q2[j] = row_from_below<2>(gs[ai][m - 1][n][j]); } }
;                     else { const int slot = (2 * ai + wr) ? (2 * ai + wr) : 4 + (u.pm & 1);
;                         q1 = *(const LAS f32x4*)(hal + halo_idx(slot, wc, 1, ci0 + 4 * n)); q2 = *(const LAS f32x4*)(hal + halo_idx(slot, wc, fr == 0 ? 0 : 1, ci0 + 4 * n)); }
; _Pragma("unroll")
;                     for (int j = 0; j < 4; ++j) { p1[j] = row_from_below<1>(gs[ai][m][n][j]); p2[j] = row_from_below<2>(gs[ai][m][n][j]); }
;                     const f32x4 h1 = fr >= 1 ? p1 : q1, h0 = fr >= 2 ? p2 : q2;
;                     const f32x4 cv = bb[n] + w0[n] * h0 + w1[n] * h1 + w2[n] * gs[ai][m][n];
; _Pragma("unroll")
;                     for (int j = 0; j < 4; ++j) o[n][j] = cv[j] * sigm(cv[j]) * (acc[ai][1][m][n][j] * rs); }
;                 *(u32x4*)(H + hidx(r, ch0)) = pack8(o[0], o[1]); }
	v_pk_mul_f32 v[86:87], v[86:87], v[90:91] op_sel_hi:[1,0]
	s_nop 0
	v_pk_mul_f32 v[86:87], v[86:87], v[94:95]
	v_mov_b32_e32 v126, 0
	v_mov_b32_e32 v123, 0
	v_rcp_f32_e32 v95, v99
	v_mov_b32_e32 v118, 0
	v_mov_b32_e32 v117, 0
	s_nop 0
	v_mov_b32_dpp v118, v190 row_ror:2 row_mask:0xf bank_mask:0xf
	v_mov_b32_dpp v126, v191 row_ror:2 row_mask:0xf bank_mask:0xf
	v_rcp_f32_e32 v94, v98
	v_mov_b32_dpp v117, v190 row_ror:1 row_mask:0xf bank_mask:0xf
	v_mov_b32_dpp v123, v191 row_ror:1 row_mask:0xf bank_mask:0xf
	v_cndmask_b32_e64 v97, v121, v126, s[10:11]
	v_cndmask_b32_e64 v96, v119, v118, s[10:11]
	v_pk_mul_f32 v[92:93], v[92:93], v[94:95]
	v_cndmask_b32_e64 v95, v123, v120, s[8:9]
	v_cndmask_b32_e64 v94, v117, v105, s[8:9]
	v_pk_fma_f32 v[96:97], v[42:43], v[96:97], v[54:55]
	v_pk_mul_f32 v[88:89], v[88:89], v[90:91] op_sel_hi:[1,0]
	v_pk_fma_f32 v[94:95], v[46:47], v[94:95], v[96:97]
	v_pk_mul_f32 v[88:89], v[88:89], v[92:93]
	v_pk_fma_f32 v[94:95], v[190:191], v[50:51], v[94:95]
	v_mov_b32_e32 v128, 0
	v_mul_f32_e32 v92, 0xbfb8aa3b, v94
	v_exp_f32_e32 v96, v92
	v_mul_f32_e32 v92, 0xbfb8aa3b, v95
	v_exp_f32_e32 v97, v92
	v_mov_b32_e32 v132, 0
	v_mov_b32_e32 v127, 0
	v_mov_b32_dpp v128, v124 row_ror:2 row_mask:0xf bank_mask:0xf
	v_pk_add_f32 v[96:97], v[96:97], 1.0 op_sel_hi:[1,0]
	v_mov_b32_e32 v129, 0
	v_mov_b32_dpp v132, v125 row_ror:2 row_mask:0xf bank_mask:0xf
	v_mov_b32_dpp v127, v124 row_ror:1 row_mask:0xf bank_mask:0xf
	v_mov_b32_dpp v129, v125 row_ror:1 row_mask:0xf bank_mask:0xf
	v_cndmask_b32_e64 v99, v193, v132, s[10:11]
	v_cndmask_b32_e64 v98, v131, v128, s[10:11]
	v_cndmask_b32_e64 v93, v129, v192, s[8:9]
	v_cndmask_b32_e64 v92, v127, v130, s[8:9]
	v_pk_fma_f32 v[98:99], v[44:45], v[98:99], v[56:57]
	v_pk_mul_f32 v[82:83], v[82:83], v[90:91] op_sel_hi:[1,0]
	v_pk_fma_f32 v[92:93], v[48:49], v[92:93], v[98:99]
	v_rcp_f32_e32 v97, v97
	v_pk_fma_f32 v[92:93], v[124:125], v[52:53], v[92:93]
	s_nop 0
	v_mul_f32_e32 v98, 0xbfb8aa3b, v92
	v_mul_f32_e32 v99, 0xbfb8aa3b, v93
	v_exp_f32_e32 v98, v98
	v_exp_f32_e32 v99, v99
	v_rcp_f32_e32 v96, v96
	s_nop 0
	v_pk_mul_f32 v[94:95], v[94:95], v[96:97]
	v_pk_add_f32 v[98:99], v[98:99], 1.0 op_sel_hi:[1,0]
	v_pk_mul_f32 v[94:95], v[82:83], v[94:95]
	v_pk_mul_f32 v[84:85], v[84:85], v[90:91] op_sel_hi:[1,0]
	v_mov_b32_e32 v90, 0
	v_rcp_f32_e32 v83, v99
	v_rcp_f32_e32 v82, v98
	v_or_b32_e32 v96, 32, v122
	v_pk_mul_f32 v[82:83], v[92:93], v[82:83]
	v_ashrrev_i32_e32 v97, 31, v96
	v_pk_mul_f32 v[92:93], v[84:85], v[82:83]
	v_cvt_pk_bf16_f32 v82, v86, v87
	v_lshl_add_u64 v[86:87], s[48:49], 0, v[96:97]
	v_lshlrev_b64 v[86:87], 7, v[86:87]
	v_cvt_pk_bf16_f32 v83, v88, v89
	v_cvt_pk_bf16_f32 v84, v94, v95
	v_cvt_pk_bf16_f32 v85, v92, v93
	v_lshl_add_u64 v[86:87], v[156:157], 0, v[86:87]
	global_store_dwordx4 v[86:87], v[82:85], off
	v_mov_b32_e32 v86, 0
	v_mov_b32_e32 v87, 0
	v_mov_b32_e32 v82, 0
	v_mov_b32_dpp v86, v188 row_ror:2 row_mask:0xf bank_mask:0xf
	v_mov_b32_e32 v84, 0
	v_mov_b32_dpp v87, v189 row_ror:2 row_mask:0xf bank_mask:0xf
	v_mov_b32_dpp v82, v188 row_ror:1 row_mask:0xf bank_mask:0xf
	v_mov_b32_dpp v84, v189 row_ror:1 row_mask:0xf bank_mask:0xf
	v_cndmask_b32_e64 v87, v103, v87, s[10:11]
	v_cndmask_b32_e64 v86, v101, v86, s[10:11]
	v_cndmask_b32_e64 v85, v84, v102, s[8:9]
	v_cndmask_b32_e64 v84, v82, v100, s[8:9]
	v_pk_fma_f32 v[86:87], v[58:59], v[86:87], v[70:71]
	v_mov_b32_e32 v88, 0
	v_pk_fma_f32 v[84:85], v[62:63], v[84:85], v[86:87]
	v_mov_b32_dpp v90, v186 row_ror:2 row_mask:0xf bank_mask:0xf
	v_pk_fma_f32 v[84:85], v[188:189], v[66:67], v[84:85]
	v_mov_b32_dpp v88, v186 row_ror:1 row_mask:0xf bank_mask:0xf
	v_mul_f32_e32 v82, 0xbfb8aa3b, v84
	v_exp_f32_e32 v86, v82
	v_mul_f32_e32 v82, 0xbfb8aa3b, v85
	v_exp_f32_e32 v87, v82
	v_cndmask_b32_e64 v82, v88, v104, s[8:9]
	v_cndmask_b32_e64 v88, v114, v90, s[10:11]
	v_mov_b32_e32 v89, 0
	v_pk_add_f32 v[86:87], v[86:87], 1.0 op_sel_hi:[1,0]
	v_mov_b32_e32 v83, 0
	v_mov_b32_dpp v89, v187 row_ror:2 row_mask:0xf bank_mask:0xf
	s_nop 0
	v_mov_b32_dpp v83, v187 row_ror:1 row_mask:0xf bank_mask:0xf
	v_cndmask_b32_e64 v89, v116, v89, s[10:11]
	v_cndmask_b32_e64 v83, v83, v115, s[8:9]
	v_pk_fma_f32 v[88:89], v[60:61], v[88:89], v[72:73]
	v_mov_b32_e32 v95, 0
	v_pk_fma_f32 v[82:83], v[64:65], v[82:83], v[88:89]
	v_rcp_f32_e32 v87, v87
	v_pk_fma_f32 v[82:83], v[186:187], v[68:69], v[82:83]
	s_nop 0
	v_mul_f32_e32 v88, 0xbfb8aa3b, v82
	v_mul_f32_e32 v89, 0xbfb8aa3b, v83
	v_exp_f32_e32 v88, v88
	v_exp_f32_e32 v89, v89
	v_rcp_f32_e32 v86, v86
	s_nop 0
	v_pk_mul_f32 v[84:85], v[84:85], v[86:87]
	v_pk_add_f32 v[86:87], v[88:89], 1.0 op_sel_hi:[1,0]
	v_mov_b32_e32 v88, v91
	v_div_scale_f32 v89, s[0:1], v87, v87, 1.0
	v_rcp_f32_e32 v90, v89
	v_pk_mul_f32 v[78:79], v[78:79], v[88:89] op_sel_hi:[1,0]
	v_mov_b32_e32 v97, 0
	v_pk_mul_f32 v[78:79], v[78:79], v[84:85]
	v_fma_f32 v84, -v89, v90, 1.0
	v_fmac_f32_e32 v90, v84, v90
	v_div_scale_f32 v84, vcc, 1.0, v87, 1.0
	v_mul_f32_e32 v85, v84, v90
	v_fma_f32 v91, -v89, v85, v84
	v_fmac_f32_e32 v85, v91, v90
	v_fma_f32 v84, -v89, v85, v84
	v_div_scale_f32 v89, s[0:1], v86, v86, 1.0
	v_rcp_f32_e32 v91, v89
	v_div_fmas_f32 v84, v84, v90, v85
	v_div_fixup_f32 v85, v84, v87, 1.0
	v_pk_mul_f32 v[80:81], v[80:81], v[88:89] op_sel_hi:[1,0]
	v_fma_f32 v84, -v89, v91, 1.0
	v_fmac_f32_e32 v91, v84, v91
	v_div_scale_f32 v84, vcc, 1.0, v86, 1.0
	v_mul_f32_e32 v87, v84, v91
	v_fma_f32 v90, -v89, v87, v84
	v_fmac_f32_e32 v87, v90, v91
	v_fma_f32 v84, -v89, v87, v84
	v_div_fmas_f32 v84, v84, v91, v87
	v_div_fixup_f32 v84, v84, v86, 1.0
	v_pk_mul_f32 v[82:83], v[82:83], v[84:85]
	v_mov_b32_e32 v86, 0
	v_mov_b32_e32 v87, 0
; #define LAS __attribute__((address_space(3)))
; __device__ __forceinline__ size_t hidx(size_t r, int c) { return ((size_t)(c >> 6) * MTOT + r) * 64 + (c & 63); }
; __device__ __forceinline__ u32x4 pack8(const f32x4 a, const f32x4 b) { u32x4 w; w.x = cvt_pk_bf16(a[0], a[1]); w.y = cvt_pk_bf16(a[2], a[3]); w.z = cvt_pk_bf16(b[0], b[1]); w.w = cvt_pk_bf16(b[2], b[3]); return w; }
; __device__ __forceinline__ float sigm(float x) { return 1.f / (1.f + __builtin_amdgcn_exp2f(-LOG2E * x)); }
; __device__ __forceinline__ int halo_idx(int slot, int wc, int row, int ci) { return ((slot * 4 + wc) * 2 + row) * 32 + ci; }
;     __device__ __forceinline__ void operator()(const f32x4 (&acc)[2][2][4][2], const Unit& u, int wr, int wc, int fr, int fq) const {
;     ...
;             for (int m = 0; m < 4; ++m) { const int r = row0 + 128 * ai + 16 * m; const float rs = rsl[128 * ai + 64 * wr + 16 * m + fr]; f32x4 o[2];
; _Pragma("unroll")
;                 for (int n = 0; n < 2; ++n) { f32x4 p1, p2, q1, q2;
;                     if (m > 0) {
; _Pragma("unroll")
;                         for (int j = 0; j < 4; ++j) { q1[j] = row_from_below<1>(gs[ai][m - 1][n][j]); q2[j] = row_from_below<2>(gs[ai][m - 1][n][j]); } }
;                     else { const int slot = (2 * ai + wr) ? (2 * ai + wr) : 4 + (u.pm & 1);
;                         q1 = *(const LAS f32x4*)(hal + halo_idx(slot, wc, 1, ci0 + 4 * n)); q2 = *(const LAS f32x4*)(hal + halo_idx(slot, wc, fr == 0 ? 0 : 1, ci0 + 4 * n)); }
; _Pragma("unroll")
;                     for (int j = 0; j < 4; ++j) { p1[j] = row_from_below<1>(gs[ai][m][n][j]); p2[j] = row_from_below<2>(gs[ai][m][n][j]); }
;                     const f32x4 h1 = fr >= 1 ? p1 : q1, h0 = fr >= 2 ? p2 : q2;
;                     const f32x4 cv = bb[n] + w0[n] * h0 + w1[n] * h1 + w2[n] * gs[ai][m][n];
; _Pragma("unroll")
;                     for (int j = 0; j < 4; ++j) o[n][j] = cv[j] * sigm(cv[j]) * (acc[ai][1][m][n][j] * rs); }
;                 *(u32x4*)(H + hidx(r, ch0)) = pack8(o[0], o[1]); }
	v_pk_mul_f32 v[80:81], v[80:81], v[82:83]
	v_mov_b32_e32 v82, 0
	v_mov_b32_dpp v86, v180 row_ror:2 row_mask:0xf bank_mask:0xf
	v_mov_b32_e32 v84, 0
	v_mov_b32_dpp v87, v181 row_ror:2 row_mask:0xf bank_mask:0xf
	v_mov_b32_dpp v82, v180 row_ror:1 row_mask:0xf bank_mask:0xf
	v_mov_b32_dpp v84, v181 row_ror:1 row_mask:0xf bank_mask:0xf
	v_cndmask_b32_e64 v87, v126, v87, s[10:11]
	v_cndmask_b32_e64 v86, v118, v86, s[10:11]
	v_cndmask_b32_e64 v85, v84, v123, s[8:9]
	v_cndmask_b32_e64 v84, v82, v117, s[8:9]
	v_pk_fma_f32 v[86:87], v[42:43], v[86:87], v[54:55]
	v_mov_b32_e32 v89, 0
	v_pk_fma_f32 v[84:85], v[46:47], v[84:85], v[86:87]
	v_mov_b32_e32 v90, 0
	v_pk_fma_f32 v[84:85], v[180:181], v[50:51], v[84:85]
	v_mov_b32_dpp v89, v178 row_ror:1 row_mask:0xf bank_mask:0xf
	v_mul_f32_e32 v82, 0xbfb8aa3b, v84
	v_exp_f32_e32 v86, v82
	v_mul_f32_e32 v82, 0xbfb8aa3b, v85
	v_exp_f32_e32 v87, v82
	v_cndmask_b32_e64 v82, v89, v127, s[8:9]
	v_mov_b32_e32 v91, 0
	v_mov_b32_dpp v90, v178 row_ror:2 row_mask:0xf bank_mask:0xf
	v_pk_add_f32 v[86:87], v[86:87], 1.0 op_sel_hi:[1,0]
	v_mov_b32_e32 v83, 0
	v_mov_b32_dpp v91, v179 row_ror:2 row_mask:0xf bank_mask:0xf
	s_nop 0
	v_mov_b32_dpp v83, v179 row_ror:1 row_mask:0xf bank_mask:0xf
	v_cndmask_b32_e64 v91, v132, v91, s[10:11]
	v_cndmask_b32_e64 v90, v128, v90, s[10:11]
	v_cndmask_b32_e64 v83, v83, v129, s[8:9]
	v_pk_fma_f32 v[90:91], v[44:45], v[90:91], v[56:57]
	v_mov_b32_e32 v94, 0
	v_pk_fma_f32 v[82:83], v[48:49], v[82:83], v[90:91]
	v_rcp_f32_e32 v87, v87
	v_pk_fma_f32 v[82:83], v[178:179], v[52:53], v[82:83]
	s_nop 0
	v_mul_f32_e32 v90, 0xbfb8aa3b, v82
	v_mul_f32_e32 v91, 0xbfb8aa3b, v83
	v_exp_f32_e32 v90, v90
	v_exp_f32_e32 v91, v91
	v_rcp_f32_e32 v86, v86
	s_nop 0
	v_pk_mul_f32 v[84:85], v[84:85], v[86:87]
	v_pk_add_f32 v[90:91], v[90:91], 1.0 op_sel_hi:[1,0]
	v_mov_b32_dpp v95, v184 row_ror:2 row_mask:0xf bank_mask:0xf
	v_div_scale_f32 v89, s[0:1], v91, v91, 1.0
	v_rcp_f32_e32 v92, v89
	v_pk_mul_f32 v[74:75], v[74:75], v[88:89] op_sel_hi:[1,0]
	v_mov_b32_e32 v96, 0
	v_pk_mul_f32 v[84:85], v[74:75], v[84:85]
	v_fma_f32 v74, -v89, v92, 1.0
	v_fmac_f32_e32 v92, v74, v92
	v_div_scale_f32 v74, vcc, 1.0, v91, 1.0
	v_mul_f32_e32 v75, v74, v92
	v_fma_f32 v86, -v89, v75, v74
	v_fmac_f32_e32 v75, v86, v92
	v_div_scale_f32 v86, s[0:1], v90, v90, 1.0
	v_rcp_f32_e32 v87, v86
	v_fma_f32 v74, -v89, v75, v74
	v_div_fmas_f32 v74, v74, v92, v75
	v_div_fixup_f32 v75, v74, v91, 1.0
	v_fma_f32 v74, -v86, v87, 1.0
	v_fmac_f32_e32 v87, v74, v87
	v_div_scale_f32 v74, vcc, 1.0, v90, 1.0
	v_mul_f32_e32 v89, v74, v87
	v_fma_f32 v91, -v86, v89, v74
	v_fmac_f32_e32 v89, v91, v87
	v_fma_f32 v74, -v86, v89, v74
	v_div_fmas_f32 v74, v74, v87, v89
	v_div_fixup_f32 v74, v74, v90, 1.0
	v_or_b32_e32 v86, 48, v122
	v_pk_mul_f32 v[74:75], v[82:83], v[74:75]
	v_pk_mul_f32 v[76:77], v[76:77], v[88:89] op_sel_hi:[1,0]
	v_ashrrev_i32_e32 v87, 31, v86
	v_pk_mul_f32 v[82:83], v[76:77], v[74:75]
	v_cvt_pk_bf16_f32 v74, v78, v79
	v_lshl_add_u64 v[78:79], s[48:49], 0, v[86:87]
	v_lshlrev_b64 v[78:79], 7, v[78:79]
	v_cvt_pk_bf16_f32 v75, v80, v81
	v_cvt_pk_bf16_f32 v76, v84, v85
	v_cvt_pk_bf16_f32 v77, v82, v83
	v_lshl_add_u64 v[78:79], v[156:157], 0, v[78:79]
	global_store_dwordx4 v[78:79], v[74:77], off
	ds_read_b32 v84, v146
	v_mov_b32_dpp v97, v185 row_ror:2 row_mask:0xf bank_mask:0xf
	v_add_u32_e32 v74, s74, v204
	ds_read_b128 v[88:91], v74 offset:128
	ds_read_b128 v[74:77], v74 offset:144
	ds_read_b128 v[100:103], v217
	v_mov_b32_dpp v94, v184 row_ror:1 row_mask:0xf bank_mask:0xf
	v_mov_b32_dpp v96, v185 row_ror:1 row_mask:0xf bank_mask:0xf
	v_mov_b32_e32 v87, 0
	s_waitcnt lgkmcnt(2)
	v_cndmask_b32_e64 v89, v96, v89, s[8:9]
	s_waitcnt lgkmcnt(0)
	v_cndmask_b32_e64 v93, v101, v97, s[10:11]
	v_cndmask_b32_e64 v92, v100, v95, s[10:11]
	v_cndmask_b32_e64 v88, v94, v88, s[8:9]
	v_pk_fma_f32 v[92:93], v[58:59], v[92:93], v[70:71]
	v_mov_b32_e32 v98, 0
	v_pk_fma_f32 v[88:89], v[62:63], v[88:89], v[92:93]
	v_mov_b32_dpp v87, v182 row_ror:2 row_mask:0xf bank_mask:0xf
	v_pk_fma_f32 v[92:93], v[184:185], v[66:67], v[88:89]
	v_mov_b32_dpp v98, v183 row_ror:2 row_mask:0xf bank_mask:0xf
	v_mul_f32_e32 v83, 0xbfb8aa3b, v92
	v_exp_f32_e32 v88, v83
	v_mul_f32_e32 v83, 0xbfb8aa3b, v93
	v_exp_f32_e32 v89, v83
	v_cndmask_b32_e64 v101, v103, v98, s[10:11]
	v_cndmask_b32_e64 v100, v102, v87, s[10:11]
	v_mov_b32_e32 v85, 0
	v_pk_add_f32 v[102:103], v[88:89], 1.0 op_sel_hi:[1,0]
	v_mov_b32_e32 v99, 0
	v_mov_b32_dpp v85, v182 row_ror:1 row_mask:0xf bank_mask:0xf
	s_nop 0
	v_mov_b32_dpp v99, v183 row_ror:1 row_mask:0xf bank_mask:0xf
	v_cndmask_b32_e64 v91, v99, v91, s[8:9]
	v_cndmask_b32_e64 v90, v85, v90, s[8:9]
	v_pk_fma_f32 v[88:89], v[60:61], v[100:101], v[72:73]
	v_pk_mul_f32 v[30:31], v[30:31], v[84:85] op_sel_hi:[1,0]
	v_pk_fma_f32 v[88:89], v[64:65], v[90:91], v[88:89]
	v_rcp_f32_e32 v91, v103
	v_pk_fma_f32 v[88:89], v[182:183], v[68:69], v[88:89]
	s_nop 0
	v_mul_f32_e32 v90, 0xbfb8aa3b, v88
	v_exp_f32_e32 v100, v90
	v_mul_f32_e32 v90, 0xbfb8aa3b, v89
	v_exp_f32_e32 v101, v90
	v_rcp_f32_e32 v90, v102
	s_nop 0
	v_pk_mul_f32 v[92:93], v[92:93], v[90:91]
	v_pk_add_f32 v[90:91], v[100:101], 1.0 op_sel_hi:[1,0]
	v_pk_mul_f32 v[30:31], v[30:31], v[92:93]
	ds_read_b128 v[78:81], v217 offset:16
	ds_read_b32 v86, v214 offset:704
	v_pk_mul_f32 v[32:33], v[32:33], v[84:85] op_sel_hi:[1,0]
	v_rcp_f32_e32 v91, v91
	v_pk_mul_f32 v[26:27], v[26:27], v[84:85] op_sel_hi:[1,0]
	v_rcp_f32_e32 v90, v90
	s_nop 0
	v_pk_mul_f32 v[88:89], v[88:89], v[90:91]
	v_mov_b32_e32 v91, 0
	v_pk_mul_f32 v[32:33], v[32:33], v[88:89]
	v_mov_b32_e32 v89, 0
	v_mov_b32_e32 v88, 0
	v_mov_b32_e32 v90, 0
	v_mov_b32_dpp v89, v176 row_ror:2 row_mask:0xf bank_mask:0xf
	v_mov_b32_dpp v91, v177 row_ror:2 row_mask:0xf bank_mask:0xf
	v_mov_b32_dpp v88, v176 row_ror:1 row_mask:0xf bank_mask:0xf
	v_mov_b32_dpp v90, v177 row_ror:1 row_mask:0xf bank_mask:0xf
	s_waitcnt lgkmcnt(1)
; #define LAS __attribute__((address_space(3)))
; __device__ __forceinline__ size_t hidx(size_t r, int c) { return ((size_t)(c >> 6) * MTOT + r) * 64 + (c & 63); }
; __device__ __forceinline__ u32x4 pack8(const f32x4 a, const f32x4 b) { u32x4 w; w.x = cvt_pk_bf16(a[0], a[1]); w.y = cvt_pk_bf16(a[2], a[3]); w.z = cvt_pk_bf16(b[0], b[1]); w.w = cvt_pk_bf16(b[2], b[3]); return w; }
; __device__ __forceinline__ float sigm(float x) { return 1.f / (1.f + __builtin_amdgcn_exp2f(-LOG2E * x)); }
; __device__ __forceinline__ int halo_idx(int slot, int wc, int row, int ci) { return ((slot * 4 + wc) * 2 + row) * 32 + ci; }
;     __device__ __forceinline__ void operator()(const f32x4 (&acc)[2][2][4][2], const Unit& u, int wr, int wc, int fr, int fq) const {
;     ...
;             for (int m = 0; m < 4; ++m) { const int r = row0 + 128 * ai + 16 * m; const float rs = rsl[128 * ai + 64 * wr + 16 * m + fr]; f32x4 o[2];
; _Pragma("unroll")
;                 for (int n = 0; n < 2; ++n) { f32x4 p1, p2, q1, q2;
;                     if (m > 0) {
; _Pragma("unroll")
;                         for (int j = 0; j < 4; ++j) { q1[j] = row_from_below<1>(gs[ai][m - 1][n][j]); q2[j] = row_from_below<2>(gs[ai][m - 1][n][j]); } }
;                     else { const int slot = (2 * ai + wr) ? (2 * ai + wr) : 4 + (u.pm & 1);
;                         q1 = *(const LAS f32x4*)(hal + halo_idx(slot, wc, 1, ci0 + 4 * n)); q2 = *(const LAS f32x4*)(hal + halo_idx(slot, wc, fr == 0 ? 0 : 1, ci0 + 4 * n)); }
; _Pragma("unroll")
;                     for (int j = 0; j < 4; ++j) { p1[j] = row_from_below<1>(gs[ai][m][n][j]); p2[j] = row_from_below<2>(gs[ai][m][n][j]); }
;                     const f32x4 h1 = fr >= 1 ? p1 : q1, h0 = fr >= 2 ? p2 : q2;
;                     const f32x4 cv = bb[n] + w0[n] * h0 + w1[n] * h1 + w2[n] * gs[ai][m][n];
; _Pragma("unroll")
;                     for (int j = 0; j < 4; ++j) o[n][j] = cv[j] * sigm(cv[j]) * (acc[ai][1][m][n][j] * rs); }
;                 *(u32x4*)(H + hidx(r, ch0)) = pack8(o[0], o[1]); }
	v_cndmask_b32_e64 v79, v79, v91, s[10:11]
	v_cndmask_b32_e64 v78, v78, v89, s[10:11]
	v_cndmask_b32_e64 v75, v90, v75, s[8:9]
	v_cndmask_b32_e64 v74, v88, v74, s[8:9]
	v_pk_fma_f32 v[78:79], v[42:43], v[78:79], v[54:55]
	v_mov_b32_e32 v93, 0
	v_pk_fma_f32 v[74:75], v[46:47], v[74:75], v[78:79]
	v_mov_b32_e32 v101, 0
	v_pk_fma_f32 v[74:75], v[176:177], v[50:51], v[74:75]
	v_mov_b32_e32 v92, 0
	v_mul_f32_e32 v78, 0xbfb8aa3b, v74
	v_mul_f32_e32 v79, 0xbfb8aa3b, v75
	v_exp_f32_e32 v78, v78
	v_exp_f32_e32 v79, v79
	v_mov_b32_dpp v93, v174 row_ror:2 row_mask:0xf bank_mask:0xf
	v_mov_b32_e32 v100, 0
	v_mov_b32_dpp v101, v175 row_ror:2 row_mask:0xf bank_mask:0xf
	v_pk_add_f32 v[78:79], v[78:79], 1.0 op_sel_hi:[1,0]
	v_mov_b32_dpp v92, v174 row_ror:1 row_mask:0xf bank_mask:0xf
	v_mov_b32_dpp v100, v175 row_ror:1 row_mask:0xf bank_mask:0xf
	v_cndmask_b32_e64 v81, v81, v101, s[10:11]
	v_cndmask_b32_e64 v80, v80, v93, s[10:11]
	v_cndmask_b32_e64 v77, v100, v77, s[8:9]
	v_cndmask_b32_e64 v76, v92, v76, s[8:9]
	v_pk_fma_f32 v[80:81], v[44:45], v[80:81], v[56:57]
	v_add_u32_e32 v82, 0x80, v122
	v_pk_fma_f32 v[76:77], v[48:49], v[76:77], v[80:81]
	v_rcp_f32_e32 v79, v79
	v_pk_fma_f32 v[76:77], v[174:175], v[52:53], v[76:77]
	s_nop 0
	v_mul_f32_e32 v80, 0xbfb8aa3b, v76
	v_mul_f32_e32 v81, 0xbfb8aa3b, v77
	v_exp_f32_e32 v80, v80
	v_exp_f32_e32 v81, v81
	v_rcp_f32_e32 v78, v78
	s_nop 0
	v_pk_mul_f32 v[74:75], v[74:75], v[78:79]
	v_pk_add_f32 v[80:81], v[80:81], 1.0 op_sel_hi:[1,0]
	v_pk_mul_f32 v[74:75], v[26:27], v[74:75]
	v_pk_mul_f32 v[28:29], v[28:29], v[84:85] op_sel_hi:[1,0]
	v_rcp_f32_e32 v27, v81
	v_rcp_f32_e32 v26, v80
	s_nop 0
	v_pk_mul_f32 v[26:27], v[76:77], v[26:27]
	v_ashrrev_i32_e32 v83, 31, v82
	v_pk_mul_f32 v[76:77], v[28:29], v[26:27]
	v_cvt_pk_bf16_f32 v26, v30, v31
	v_cvt_pk_bf16_f32 v29, v76, v77
	v_lshl_add_u64 v[30:31], s[48:49], 0, v[82:83]
	v_mov_b32_e32 v77, 0
	v_mov_b32_e32 v79, 0
	v_lshlrev_b64 v[30:31], 7, v[30:31]
	v_mov_b32_e32 v76, 0
	v_mov_b32_dpp v77, v110 row_ror:2 row_mask:0xf bank_mask:0xf
	v_mov_b32_e32 v78, 0
	v_mov_b32_dpp v79, v111 row_ror:2 row_mask:0xf bank_mask:0xf
	v_cvt_pk_bf16_f32 v27, v32, v33
	v_cvt_pk_bf16_f32 v28, v74, v75
	v_lshl_add_u64 v[30:31], v[156:157], 0, v[30:31]
	v_mov_b32_dpp v76, v110 row_ror:1 row_mask:0xf bank_mask:0xf
	v_mov_b32_dpp v78, v111 row_ror:1 row_mask:0xf bank_mask:0xf
	v_cndmask_b32_e64 v33, v97, v79, s[10:11]
	v_cndmask_b32_e64 v32, v95, v77, s[10:11]
	global_store_dwordx4 v[30:31], v[26:29], off
	v_cndmask_b32_e64 v31, v78, v96, s[8:9]
	v_cndmask_b32_e64 v30, v76, v94, s[8:9]
	v_pk_fma_f32 v[32:33], v[58:59], v[32:33], v[70:71]
	v_mov_b32_e32 v80, 0
	v_pk_fma_f32 v[30:31], v[62:63], v[30:31], v[32:33]
	v_mov_b32_e32 v81, 0
	v_pk_fma_f32 v[30:31], v[110:111], v[66:67], v[30:31]
	v_mov_b32_dpp v80, v112 row_ror:1 row_mask:0xf bank_mask:0xf
	v_mul_f32_e32 v28, 0xbfb8aa3b, v30
	v_exp_f32_e32 v32, v28
	v_mul_f32_e32 v28, 0xbfb8aa3b, v31
	v_exp_f32_e32 v33, v28
	v_mov_b32_e32 v83, 0
	v_cndmask_b32_e64 v28, v80, v85, s[8:9]
	v_mov_b32_dpp v81, v112 row_ror:2 row_mask:0xf bank_mask:0xf
	v_pk_add_f32 v[32:33], v[32:33], 1.0 op_sel_hi:[1,0]
	v_mov_b32_e32 v82, 0
	v_mov_b32_dpp v83, v113 row_ror:2 row_mask:0xf bank_mask:0xf
	s_nop 0
	v_mov_b32_dpp v82, v113 row_ror:1 row_mask:0xf bank_mask:0xf
	v_cndmask_b32_e64 v75, v98, v83, s[10:11]
	v_cndmask_b32_e64 v74, v87, v81, s[10:11]
	v_cndmask_b32_e64 v29, v82, v99, s[8:9]
	v_pk_fma_f32 v[74:75], v[60:61], v[74:75], v[72:73]
	ds_read2_b32 v[26:27], v214 offset0:144 offset1:160
	v_pk_fma_f32 v[28:29], v[64:65], v[28:29], v[74:75]
	v_rcp_f32_e32 v33, v33
	v_pk_fma_f32 v[28:29], v[112:113], v[68:69], v[28:29]
	s_nop 0
	v_mul_f32_e32 v74, 0xbfb8aa3b, v28
	v_mul_f32_e32 v75, 0xbfb8aa3b, v29
	v_exp_f32_e32 v74, v74
	v_exp_f32_e32 v75, v75
	v_rcp_f32_e32 v32, v32
	s_nop 0
	v_pk_mul_f32 v[30:31], v[30:31], v[32:33]
	v_pk_add_f32 v[74:75], v[74:75], 1.0 op_sel_hi:[1,0]
	s_waitcnt lgkmcnt(0)
	v_pk_mul_f32 v[22:23], v[22:23], v[26:27] op_sel_hi:[1,0]
	s_nop 0
	v_pk_mul_f32 v[22:23], v[22:23], v[30:31]
	v_mov_b32_e32 v94, 0
	v_mov_b32_e32 v87, 0
	v_rcp_f32_e32 v31, v75
	v_mov_b32_e32 v85, 0
	v_mov_b32_e32 v84, 0
	s_nop 0
	v_mov_b32_dpp v85, v106 row_ror:2 row_mask:0xf bank_mask:0xf
	v_mov_b32_dpp v94, v107 row_ror:2 row_mask:0xf bank_mask:0xf
	v_rcp_f32_e32 v30, v74
	v_mov_b32_dpp v84, v106 row_ror:1 row_mask:0xf bank_mask:0xf
	v_mov_b32_dpp v87, v107 row_ror:1 row_mask:0xf bank_mask:0xf
	v_cndmask_b32_e64 v33, v91, v94, s[10:11]
	v_cndmask_b32_e64 v32, v89, v85, s[10:11]
	v_pk_mul_f32 v[28:29], v[28:29], v[30:31]
	v_cndmask_b32_e64 v31, v87, v90, s[8:9]
	v_cndmask_b32_e64 v30, v84, v88, s[8:9]
	v_pk_fma_f32 v[32:33], v[42:43], v[32:33], v[54:55]
	v_pk_mul_f32 v[24:25], v[24:25], v[26:27] op_sel_hi:[1,0]
	v_pk_fma_f32 v[30:31], v[46:47], v[30:31], v[32:33]
	v_pk_mul_f32 v[24:25], v[24:25], v[28:29]
	v_pk_fma_f32 v[30:31], v[106:107], v[50:51], v[30:31]
	v_mov_b32_e32 v96, 0
	v_mul_f32_e32 v28, 0xbfb8aa3b, v30
	v_exp_f32_e32 v32, v28
	v_mul_f32_e32 v28, 0xbfb8aa3b, v31
	v_exp_f32_e32 v33, v28
	v_mov_b32_e32 v98, 0
	v_mov_b32_e32 v95, 0
	v_mov_b32_dpp v96, v108 row_ror:2 row_mask:0xf bank_mask:0xf
	v_pk_add_f32 v[32:33], v[32:33], 1.0 op_sel_hi:[1,0]
	v_mov_b32_e32 v97, 0
	v_mov_b32_dpp v98, v109 row_ror:2 row_mask:0xf bank_mask:0xf
	v_mov_b32_dpp v95, v108 row_ror:1 row_mask:0xf bank_mask:0xf
	v_mov_b32_dpp v97, v109 row_ror:1 row_mask:0xf bank_mask:0xf
	v_cndmask_b32_e64 v75, v101, v98, s[10:11]
	v_cndmask_b32_e64 v74, v93, v96, s[10:11]
	v_cndmask_b32_e64 v29, v97, v100, s[8:9]
	v_cndmask_b32_e64 v28, v95, v92, s[8:9]
	v_pk_fma_f32 v[74:75], v[44:45], v[74:75], v[56:57]
; #define LAS __attribute__((address_space(3)))
; __device__ __forceinline__ size_t hidx(size_t r, int c) { return ((size_t)(c >> 6) * MTOT + r) * 64 + (c & 63); }
; __device__ __forceinline__ u32x4 pack8(const f32x4 a, const f32x4 b) { u32x4 w; w.x = cvt_pk_bf16(a[0], a[1]); w.y = cvt_pk_bf16(a[2], a[3]); w.z = cvt_pk_bf16(b[0], b[1]); w.w = cvt_pk_bf16(b[2], b[3]); return w; }
; __device__ __forceinline__ float sigm(float x) { return 1.f / (1.f + __builtin_amdgcn_exp2f(-LOG2E * x)); }
; __device__ __forceinline__ int halo_idx(int slot, int wc, int row, int ci) { return ((slot * 4 + wc) * 2 + row) * 32 + ci; }
;     __device__ __forceinline__ void operator()(const f32x4 (&acc)[2][2][4][2], const Unit& u, int wr, int wc, int fr, int fq) const {
;     ...
;             for (int m = 0; m < 4; ++m) { const int r = row0 + 128 * ai + 16 * m; const float rs = rsl[128 * ai + 64 * wr + 16 * m + fr]; f32x4 o[2];
; _Pragma("unroll")
;                 for (int n = 0; n < 2; ++n) { f32x4 p1, p2, q1, q2;
;                     if (m > 0) {
; _Pragma("unroll")
;                         for (int j = 0; j < 4; ++j) { q1[j] = row_from_below<1>(gs[ai][m - 1][n][j]); q2[j] = row_from_below<2>(gs[ai][m - 1][n][j]); } }
;                     else { const int slot = (2 * ai + wr) ? (2 * ai + wr) : 4 + (u.pm & 1);
;                         q1 = *(const LAS f32x4*)(hal + halo_idx(slot, wc, 1, ci0 + 4 * n)); q2 = *(const LAS f32x4*)(hal + halo_idx(slot, wc, fr == 0 ? 0 : 1, ci0 + 4 * n)); }
; _Pragma("unroll")
;                     for (int j = 0; j < 4; ++j) { p1[j] = row_from_below<1>(gs[ai][m][n][j]); p2[j] = row_from_below<2>(gs[ai][m][n][j]); }
;                     const f32x4 h1 = fr >= 1 ? p1 : q1, h0 = fr >= 2 ? p2 : q2;
;                     const f32x4 cv = bb[n] + w0[n] * h0 + w1[n] * h1 + w2[n] * gs[ai][m][n];
; _Pragma("unroll")
;                     for (int j = 0; j < 4; ++j) o[n][j] = cv[j] * sigm(cv[j]) * (acc[ai][1][m][n][j] * rs); }
;                 *(u32x4*)(H + hidx(r, ch0)) = pack8(o[0], o[1]); }
	v_pk_mul_f32 v[18:19], v[18:19], v[26:27] op_sel_hi:[1,0]
	v_pk_fma_f32 v[28:29], v[48:49], v[28:29], v[74:75]
	v_rcp_f32_e32 v33, v33
	v_pk_fma_f32 v[28:29], v[108:109], v[52:53], v[28:29]
	s_nop 0
	v_mul_f32_e32 v74, 0xbfb8aa3b, v28
	v_mul_f32_e32 v75, 0xbfb8aa3b, v29
	v_exp_f32_e32 v74, v74
	v_exp_f32_e32 v75, v75
	v_rcp_f32_e32 v32, v32
	s_nop 0
	v_pk_mul_f32 v[30:31], v[30:31], v[32:33]
	v_pk_add_f32 v[74:75], v[74:75], 1.0 op_sel_hi:[1,0]
	v_pk_mul_f32 v[30:31], v[18:19], v[30:31]
	v_pk_mul_f32 v[20:21], v[20:21], v[26:27] op_sel_hi:[1,0]
	v_pk_mul_f32 v[6:7], v[6:7], v[86:87] op_sel_hi:[1,0]
	v_pk_mul_f32 v[8:9], v[8:9], v[86:87] op_sel_hi:[1,0]
	v_rcp_f32_e32 v19, v75
	v_rcp_f32_e32 v18, v74
	v_add_u32_e32 v32, 0x90, v122
	v_pk_mul_f32 v[18:19], v[28:29], v[18:19]
	v_ashrrev_i32_e32 v33, 31, v32
	v_pk_mul_f32 v[28:29], v[20:21], v[18:19]
	v_cvt_pk_bf16_f32 v18, v22, v23
	v_lshl_add_u64 v[22:23], s[48:49], 0, v[32:33]
	v_cvt_pk_bf16_f32 v20, v30, v31
	v_cvt_pk_bf16_f32 v21, v28, v29
	v_lshlrev_b64 v[22:23], 7, v[22:23]
	v_mov_b32_e32 v29, 0
	v_mov_b32_e32 v31, 0
	v_cvt_pk_bf16_f32 v19, v24, v25
	v_lshl_add_u64 v[22:23], v[156:157], 0, v[22:23]
	v_mov_b32_e32 v28, 0
	v_mov_b32_dpp v29, v172 row_ror:2 row_mask:0xf bank_mask:0xf
	v_mov_b32_e32 v30, 0
	v_mov_b32_dpp v31, v173 row_ror:2 row_mask:0xf bank_mask:0xf
	global_store_dwordx4 v[22:23], v[18:21], off
	v_mov_b32_dpp v28, v172 row_ror:1 row_mask:0xf bank_mask:0xf
	v_mov_b32_dpp v30, v173 row_ror:1 row_mask:0xf bank_mask:0xf
	v_cndmask_b32_e64 v23, v79, v31, s[10:11]
	v_cndmask_b32_e64 v22, v77, v29, s[10:11]
	v_cndmask_b32_e64 v21, v30, v78, s[8:9]
	v_cndmask_b32_e64 v20, v28, v76, s[8:9]
	v_pk_fma_f32 v[22:23], v[58:59], v[22:23], v[70:71]
	v_mov_b32_e32 v33, 0
	v_pk_fma_f32 v[20:21], v[62:63], v[20:21], v[22:23]
	v_mov_b32_e32 v75, 0
	v_pk_fma_f32 v[20:21], v[172:173], v[66:67], v[20:21]
	v_mov_b32_e32 v32, 0
	v_mul_f32_e32 v18, 0xbfb8aa3b, v20
	v_exp_f32_e32 v22, v18
	v_mul_f32_e32 v18, 0xbfb8aa3b, v21
	v_exp_f32_e32 v23, v18
	v_mov_b32_dpp v33, v170 row_ror:2 row_mask:0xf bank_mask:0xf
	v_mov_b32_e32 v74, 0
	v_mov_b32_dpp v75, v171 row_ror:2 row_mask:0xf bank_mask:0xf
	v_pk_add_f32 v[22:23], v[22:23], 1.0 op_sel_hi:[1,0]
	v_mov_b32_dpp v32, v170 row_ror:1 row_mask:0xf bank_mask:0xf
	v_mov_b32_dpp v74, v171 row_ror:1 row_mask:0xf bank_mask:0xf
	v_cndmask_b32_e64 v25, v83, v75, s[10:11]
	v_cndmask_b32_e64 v24, v81, v33, s[10:11]
	v_cndmask_b32_e64 v19, v74, v82, s[8:9]
	v_cndmask_b32_e64 v18, v32, v80, s[8:9]
	v_pk_fma_f32 v[24:25], v[60:61], v[24:25], v[72:73]
	v_mov_b32_e32 v78, 0
	v_pk_fma_f32 v[18:19], v[64:65], v[18:19], v[24:25]
	v_rcp_f32_e32 v23, v23
	v_pk_fma_f32 v[18:19], v[170:171], v[68:69], v[18:19]
	s_nop 0
	v_mul_f32_e32 v24, 0xbfb8aa3b, v18
	v_mul_f32_e32 v25, 0xbfb8aa3b, v19
	v_exp_f32_e32 v24, v24
	v_exp_f32_e32 v25, v25
	v_rcp_f32_e32 v22, v22
	s_nop 0
	v_pk_mul_f32 v[20:21], v[20:21], v[22:23]
	v_pk_add_f32 v[22:23], v[24:25], 1.0 op_sel_hi:[1,0]
	v_mov_b32_e32 v24, v27
	v_div_scale_f32 v25, s[0:1], v23, v23, 1.0
	v_rcp_f32_e32 v26, v25
	v_pk_mul_f32 v[14:15], v[14:15], v[24:25] op_sel_hi:[1,0]
	v_mov_b32_e32 v76, 0
	v_pk_mul_f32 v[14:15], v[14:15], v[20:21]
	v_fma_f32 v20, -v25, v26, 1.0
	v_fmac_f32_e32 v26, v20, v26
	v_div_scale_f32 v20, vcc, 1.0, v23, 1.0
	v_mul_f32_e32 v21, v20, v26
	v_fma_f32 v27, -v25, v21, v20
	v_fmac_f32_e32 v21, v27, v26
	v_fma_f32 v20, -v25, v21, v20
	v_div_scale_f32 v25, s[0:1], v22, v22, 1.0
	v_rcp_f32_e32 v27, v25
	v_div_fmas_f32 v20, v20, v26, v21
	v_div_fixup_f32 v21, v20, v23, 1.0
	v_pk_mul_f32 v[16:17], v[16:17], v[24:25] op_sel_hi:[1,0]
	v_fma_f32 v20, -v25, v27, 1.0
	v_fmac_f32_e32 v27, v20, v27
	v_div_scale_f32 v20, vcc, 1.0, v22, 1.0
	v_mul_f32_e32 v23, v20, v27
	v_fma_f32 v26, -v25, v23, v20
	v_fmac_f32_e32 v23, v26, v27
	v_fma_f32 v20, -v25, v23, v20
	v_div_fmas_f32 v20, v20, v27, v23
	v_mov_b32_e32 v25, 0
	v_mov_b32_dpp v76, v168 row_ror:2 row_mask:0xf bank_mask:0xf
	v_mov_b32_e32 v77, 0
	v_mov_b32_dpp v78, v169 row_ror:2 row_mask:0xf bank_mask:0xf
	v_div_fixup_f32 v20, v20, v22, 1.0
	v_mov_b32_dpp v25, v168 row_ror:1 row_mask:0xf bank_mask:0xf
	v_mov_b32_dpp v77, v169 row_ror:1 row_mask:0xf bank_mask:0xf
	v_cndmask_b32_e64 v23, v94, v78, s[10:11]
	v_cndmask_b32_e64 v22, v85, v76, s[10:11]
	v_pk_mul_f32 v[18:19], v[18:19], v[20:21]
	v_cndmask_b32_e64 v21, v77, v87, s[8:9]
	v_cndmask_b32_e64 v20, v25, v84, s[8:9]
	v_pk_fma_f32 v[22:23], v[42:43], v[22:23], v[54:55]
	v_pk_mul_f32 v[16:17], v[16:17], v[18:19]
	v_pk_fma_f32 v[20:21], v[46:47], v[20:21], v[22:23]
	v_mov_b32_e32 v80, 0
	v_pk_fma_f32 v[20:21], v[168:169], v[50:51], v[20:21]
	v_mov_b32_e32 v82, 0
	v_mul_f32_e32 v18, 0xbfb8aa3b, v20
	v_exp_f32_e32 v22, v18
	v_mul_f32_e32 v18, 0xbfb8aa3b, v21
	v_exp_f32_e32 v23, v18
	v_mov_b32_e32 v79, 0
	v_mov_b32_dpp v80, v166 row_ror:2 row_mask:0xf bank_mask:0xf
	v_mov_b32_e32 v81, 0
	v_pk_add_f32 v[22:23], v[22:23], 1.0 op_sel_hi:[1,0]
	v_mov_b32_dpp v82, v167 row_ror:2 row_mask:0xf bank_mask:0xf
	v_mov_b32_dpp v79, v166 row_ror:1 row_mask:0xf bank_mask:0xf
	v_mov_b32_dpp v81, v167 row_ror:1 row_mask:0xf bank_mask:0xf
	v_cndmask_b32_e64 v27, v98, v82, s[10:11]
	v_cndmask_b32_e64 v26, v96, v80, s[10:11]
	v_cndmask_b32_e64 v19, v81, v97, s[8:9]
	v_cndmask_b32_e64 v18, v79, v95, s[8:9]
	v_pk_fma_f32 v[26:27], v[44:45], v[26:27], v[56:57]
	v_pk_mul_f32 v[10:11], v[10:11], v[24:25] op_sel_hi:[1,0]
	v_pk_fma_f32 v[18:19], v[48:49], v[18:19], v[26:27]
	v_rcp_f32_e32 v23, v23
	v_pk_fma_f32 v[18:19], v[166:167], v[52:53], v[18:19]
	s_nop 0
	v_mul_f32_e32 v26, 0xbfb8aa3b, v18
	v_mul_f32_e32 v27, 0xbfb8aa3b, v19
	v_exp_f32_e32 v26, v26
; #define LAS __attribute__((address_space(3)))
; __device__ __forceinline__ size_t hidx(size_t r, int c) { return ((size_t)(c >> 6) * MTOT + r) * 64 + (c & 63); }
; __device__ __forceinline__ u32x4 pack8(const f32x4 a, const f32x4 b) { u32x4 w; w.x = cvt_pk_bf16(a[0], a[1]); w.y = cvt_pk_bf16(a[2], a[3]); w.z = cvt_pk_bf16(b[0], b[1]); w.w = cvt_pk_bf16(b[2], b[3]); return w; }
; __device__ __forceinline__ float sigm(float x) { return 1.f / (1.f + __builtin_amdgcn_exp2f(-LOG2E * x)); }
; __device__ __forceinline__ int halo_idx(int slot, int wc, int row, int ci) { return ((slot * 4 + wc) * 2 + row) * 32 + ci; }
;     __device__ __forceinline__ void operator()(const f32x4 (&acc)[2][2][4][2], const Unit& u, int wr, int wc, int fr, int fq) const {
;     ...
;             for (int m = 0; m < 4; ++m) { const int r = row0 + 128 * ai + 16 * m; const float rs = rsl[128 * ai + 64 * wr + 16 * m + fr]; f32x4 o[2];
; _Pragma("unroll")
;                 for (int n = 0; n < 2; ++n) { f32x4 p1, p2, q1, q2;
;                     if (m > 0) {
; _Pragma("unroll")
;                         for (int j = 0; j < 4; ++j) { q1[j] = row_from_below<1>(gs[ai][m - 1][n][j]); q2[j] = row_from_below<2>(gs[ai][m - 1][n][j]); } }
;                     else { const int slot = (2 * ai + wr) ? (2 * ai + wr) : 4 + (u.pm & 1);
;                         q1 = *(const LAS f32x4*)(hal + halo_idx(slot, wc, 1, ci0 + 4 * n)); q2 = *(const LAS f32x4*)(hal + halo_idx(slot, wc, fr == 0 ? 0 : 1, ci0 + 4 * n)); }
; _Pragma("unroll")
;                     for (int j = 0; j < 4; ++j) { p1[j] = row_from_below<1>(gs[ai][m][n][j]); p2[j] = row_from_below<2>(gs[ai][m][n][j]); }
;                     const f32x4 h1 = fr >= 1 ? p1 : q1, h0 = fr >= 2 ? p2 : q2;
;                     const f32x4 cv = bb[n] + w0[n] * h0 + w1[n] * h1 + w2[n] * gs[ai][m][n];
; _Pragma("unroll")
;                     for (int j = 0; j < 4; ++j) o[n][j] = cv[j] * sigm(cv[j]) * (acc[ai][1][m][n][j] * rs); }
;                 *(u32x4*)(H + hidx(r, ch0)) = pack8(o[0], o[1]); }
	v_exp_f32_e32 v27, v27
	v_rcp_f32_e32 v22, v22
	s_nop 0
	v_pk_mul_f32 v[20:21], v[20:21], v[22:23]
	v_pk_add_f32 v[26:27], v[26:27], 1.0 op_sel_hi:[1,0]
	v_pk_mul_f32 v[20:21], v[10:11], v[20:21]
	v_pk_mul_f32 v[12:13], v[12:13], v[24:25] op_sel_hi:[1,0]
	v_pk_mul_f32 v[2:3], v[2:3], v[86:87] op_sel_hi:[1,0]
	v_pk_mul_f32 v[4:5], v[4:5], v[86:87] op_sel_hi:[1,0]
	v_div_scale_f32 v22, s[0:1], v26, v26, 1.0
	v_rcp_f32_e32 v23, v22
	v_rcp_f32_e32 v11, v27
	v_fma_f32 v10, -v22, v23, 1.0
	v_fmac_f32_e32 v23, v10, v23
	v_div_scale_f32 v10, vcc, 1.0, v26, 1.0
	v_mul_f32_e32 v27, v10, v23
	v_fma_f32 v83, -v22, v27, v10
	v_fmac_f32_e32 v27, v83, v23
	v_fma_f32 v10, -v22, v27, v10
	v_div_fmas_f32 v10, v10, v23, v27
	v_div_fixup_f32 v10, v10, v26, 1.0
	v_add_u32_e32 v22, 0xa0, v122
	v_pk_mul_f32 v[10:11], v[18:19], v[10:11]
	v_ashrrev_i32_e32 v23, 31, v22
	v_pk_mul_f32 v[18:19], v[12:13], v[10:11]
	v_cvt_pk_bf16_f32 v10, v14, v15
	v_lshl_add_u64 v[14:15], s[48:49], 0, v[22:23]
	v_lshlrev_b64 v[14:15], 7, v[14:15]
	v_cvt_pk_bf16_f32 v11, v16, v17
	v_cvt_pk_bf16_f32 v12, v20, v21
	v_cvt_pk_bf16_f32 v13, v18, v19
	v_lshl_add_u64 v[14:15], v[156:157], 0, v[14:15]
	global_store_dwordx4 v[14:15], v[10:13], off
	v_mov_b32_e32 v14, 0
	v_mov_b32_e32 v15, 0
	v_mov_b32_e32 v10, 0
	v_mov_b32_dpp v14, v38 row_ror:2 row_mask:0xf bank_mask:0xf
	v_mov_b32_e32 v12, 0
	v_mov_b32_dpp v15, v39 row_ror:2 row_mask:0xf bank_mask:0xf
	v_mov_b32_dpp v10, v38 row_ror:1 row_mask:0xf bank_mask:0xf
	v_mov_b32_dpp v12, v39 row_ror:1 row_mask:0xf bank_mask:0xf
	v_cndmask_b32_e64 v15, v31, v15, s[10:11]
	v_cndmask_b32_e64 v14, v29, v14, s[10:11]
	v_cndmask_b32_e64 v13, v12, v30, s[8:9]
	v_cndmask_b32_e64 v12, v10, v28, s[8:9]
	v_pk_fma_f32 v[14:15], v[58:59], v[14:15], v[70:71]
	v_mov_b32_e32 v16, 0
	v_pk_fma_f32 v[12:13], v[62:63], v[12:13], v[14:15]
	v_mov_b32_e32 v18, 0
	v_pk_fma_f32 v[12:13], v[38:39], v[66:67], v[12:13]
	v_mov_b32_dpp v16, v40 row_ror:1 row_mask:0xf bank_mask:0xf
	v_mul_f32_e32 v10, 0xbfb8aa3b, v12
	v_exp_f32_e32 v14, v10
	v_mul_f32_e32 v10, 0xbfb8aa3b, v13
	v_exp_f32_e32 v15, v10
	v_mov_b32_dpp v18, v40 row_ror:2 row_mask:0xf bank_mask:0xf
	v_cndmask_b32_e64 v10, v16, v32, s[8:9]
	v_cndmask_b32_e64 v16, v33, v18, s[10:11]
	v_pk_add_f32 v[14:15], v[14:15], 1.0 op_sel_hi:[1,0]
	v_mov_b32_e32 v17, 0
	v_mov_b32_e32 v11, 0
	s_nop 0
	v_mov_b32_dpp v17, v41 row_ror:2 row_mask:0xf bank_mask:0xf
	v_cndmask_b32_e64 v17, v75, v17, s[10:11]
	v_mov_b32_dpp v11, v41 row_ror:1 row_mask:0xf bank_mask:0xf
	v_cndmask_b32_e64 v11, v11, v74, s[8:9]
	v_pk_fma_f32 v[16:17], v[60:61], v[16:17], v[72:73]
	s_nop 0
	v_pk_fma_f32 v[10:11], v[64:65], v[10:11], v[16:17]
	v_rcp_f32_e32 v15, v15
	v_pk_fma_f32 v[10:11], v[40:41], v[68:69], v[10:11]
	s_nop 0
	v_mul_f32_e32 v16, 0xbfb8aa3b, v10
	v_mul_f32_e32 v17, 0xbfb8aa3b, v11
	v_exp_f32_e32 v16, v16
	v_exp_f32_e32 v17, v17
	v_rcp_f32_e32 v14, v14
	s_nop 0
	v_pk_mul_f32 v[12:13], v[12:13], v[14:15]
	v_pk_add_f32 v[16:17], v[16:17], 1.0 op_sel_hi:[1,0]
	v_pk_mul_f32 v[6:7], v[6:7], v[12:13]
	s_nop 0
	v_rcp_f32_e32 v13, v17
	v_rcp_f32_e32 v12, v16
	s_nop 0
	v_pk_mul_f32 v[10:11], v[10:11], v[12:13]
	v_mov_b32_e32 v14, 0
	v_mov_b32_e32 v15, 0
	v_pk_mul_f32 v[8:9], v[8:9], v[10:11]
	v_mov_b32_e32 v10, 0
	v_mov_b32_dpp v14, v34 row_ror:2 row_mask:0xf bank_mask:0xf
	v_mov_b32_e32 v12, 0
	v_mov_b32_dpp v15, v35 row_ror:2 row_mask:0xf bank_mask:0xf
	v_mov_b32_dpp v10, v34 row_ror:1 row_mask:0xf bank_mask:0xf
	v_mov_b32_dpp v12, v35 row_ror:1 row_mask:0xf bank_mask:0xf
	v_cndmask_b32_e64 v15, v78, v15, s[10:11]
	v_cndmask_b32_e64 v14, v76, v14, s[10:11]
	v_cndmask_b32_e64 v13, v12, v77, s[8:9]
	v_cndmask_b32_e64 v12, v10, v25, s[8:9]
	v_pk_fma_f32 v[14:15], v[42:43], v[14:15], v[54:55]
	v_mov_b32_e32 v16, 0
	v_pk_fma_f32 v[12:13], v[46:47], v[12:13], v[14:15]
	v_mov_b32_e32 v18, 0
	v_pk_fma_f32 v[12:13], v[34:35], v[50:51], v[12:13]
	v_mov_b32_dpp v16, v36 row_ror:1 row_mask:0xf bank_mask:0xf
	v_mul_f32_e32 v10, 0xbfb8aa3b, v12
	v_exp_f32_e32 v14, v10
	v_mul_f32_e32 v10, 0xbfb8aa3b, v13
	v_exp_f32_e32 v15, v10
	v_mov_b32_dpp v18, v36 row_ror:2 row_mask:0xf bank_mask:0xf
	v_cndmask_b32_e64 v10, v16, v79, s[8:9]
	v_cndmask_b32_e64 v16, v80, v18, s[10:11]
	v_pk_add_f32 v[14:15], v[14:15], 1.0 op_sel_hi:[1,0]
	v_mov_b32_e32 v17, 0
	v_mov_b32_e32 v11, 0
	s_nop 0
	v_mov_b32_dpp v17, v37 row_ror:2 row_mask:0xf bank_mask:0xf
	v_cndmask_b32_e64 v17, v82, v17, s[10:11]
	v_mov_b32_dpp v11, v37 row_ror:1 row_mask:0xf bank_mask:0xf
	v_cndmask_b32_e64 v11, v11, v81, s[8:9]
	v_pk_fma_f32 v[16:17], v[44:45], v[16:17], v[56:57]
	s_nop 0
	v_pk_fma_f32 v[10:11], v[48:49], v[10:11], v[16:17]
	v_div_scale_f32 v18, s[0:1], v14, v14, 1.0
	v_rcp_f32_e32 v20, v18
	v_rcp_f32_e32 v15, v15
	v_pk_fma_f32 v[10:11], v[36:37], v[52:53], v[10:11]
	v_fma_f32 v16, -v18, v20, 1.0
	v_fmac_f32_e32 v20, v16, v20
	v_div_scale_f32 v16, vcc, 1.0, v14, 1.0
	v_mul_f32_e32 v19, v16, v20
	v_fma_f32 v17, -v18, v19, v16
	v_fmac_f32_e32 v19, v17, v20
	v_fma_f32 v18, -v18, v19, v16
	v_mul_f32_e32 v16, 0xbfb8aa3b, v10
	v_mul_f32_e32 v17, 0xbfb8aa3b, v11
	v_exp_f32_e32 v16, v16
	v_exp_f32_e32 v17, v17
	v_div_fmas_f32 v18, v18, v20, v19
	v_div_fixup_f32 v14, v18, v14, 1.0
	v_pk_mul_f32 v[12:13], v[12:13], v[14:15]
	v_pk_add_f32 v[16:17], v[16:17], 1.0 op_sel_hi:[1,0]
	v_pk_mul_f32 v[12:13], v[2:3], v[12:13]
	v_div_scale_f32 v18, s[0:1], v17, v17, 1.0
	v_rcp_f32_e32 v19, v18
	s_nop 0
	v_fma_f32 v2, -v18, v19, 1.0
	v_fmac_f32_e32 v19, v2, v19
	v_div_scale_f32 v2, vcc, 1.0, v17, 1.0
	v_mul_f32_e32 v3, v2, v19
	v_fma_f32 v14, -v18, v3, v2
	v_fmac_f32_e32 v3, v14, v19
	v_div_scale_f32 v14, s[0:1], v16, v16, 1.0
	v_rcp_f32_e32 v15, v14
	v_fma_f32 v2, -v18, v3, v2
	v_div_fmas_f32 v2, v2, v19, v3
	v_div_fixup_f32 v3, v2, v17, 1.0
	v_fma_f32 v2, -v14, v15, 1.0
	v_fmac_f32_e32 v15, v2, v15
	v_div_scale_f32 v2, vcc, 1.0, v16, 1.0
	v_mul_f32_e32 v17, v2, v15
	v_fma_f32 v18, -v14, v17, v2
	v_fmac_f32_e32 v17, v18, v15
	v_fma_f32 v2, -v14, v17, v2
	v_div_fmas_f32 v2, v2, v15, v17
	v_div_fixup_f32 v2, v2, v16, 1.0
	v_add_u32_e32 v14, 0xb0, v122
	v_pk_mul_f32 v[2:3], v[10:11], v[2:3]
	v_ashrrev_i32_e32 v15, 31, v14
	v_pk_mul_f32 v[10:11], v[4:5], v[2:3]
	v_cvt_pk_bf16_f32 v2, v6, v7
	v_lshl_add_u64 v[6:7], s[48:49], 0, v[14:15]
	v_lshlrev_b64 v[6:7], 7, v[6:7]
	v_cvt_pk_bf16_f32 v3, v8, v9
	v_cvt_pk_bf16_f32 v4, v12, v13
	v_cvt_pk_bf16_f32 v5, v10, v11
	v_lshl_add_u64 v[6:7], v[156:157], 0, v[6:7]
	s_mov_b64 s[0:1], -1
	global_store_dwordx4 v[6:7], v[2:5], off
	s_cbranch_scc1 .LBB0_1073
	s_andn2_b64 vcc, exec, s[42:43]
	s_cbranch_vccnz .LBB0_1072
	s_barrier
	s_branch .LBB0_1072
